# SSM pass-1 rewritten like pass-2 (block-sparse MFMA bu, no LDS transpose) with the p->bf16 conversion streamed inside its tile loop; pooling phase rewritten: dword (2-channel) lanes, scalar row pointe
# speedup vs baseline: 1.0234x; 1.0234x over previous
; template <int PASS> __device__ void ssm_pass(const Params& P, int l, LAS unsigned char* lds) {
;     ...
;     for (int unit = blockIdx.x; unit < 256; unit += G) {
;         const int b = unit >> 4, r = (unit >> 2) & 3, g = (unit & 3) * 8 + wave;
;         const size_t tok0 = (size_t)b * SEQ + r * 1024;
;         const f32x2 a = *(const f32x2*)(lamb + (g * 64 + lane) * 2);
;         bf16x4 bf[8];
; #pragma unroll
;         for (int t = 0; t < 8; ++t) bf[t] = *(const bf16x4*)(Bfrag + ((size_t)(g * 8 + t) * 64 + lane) * 4);
;         float sr = 0.f, si = 0.f;
;         bf16x8 cf[4]; f32x4 dd;
;         if (PASS == 2) {
;             const f32x2 a1k = *(const f32x2*)(lamb1k + (g * 64 + lane) * 2);
;             for (int rr = 0; rr < r; ++rr) { const f32x2 e = *(const f32x2*)(E + ((size_t)((b * 32 + g) * 4 + rr) * 64 + lane) * 2);
;                 const float nr = a1k.x * sr - a1k.y * si + e.x, ni = a1k.x * si + a1k.y * sr + e.y; sr = nr; si = ni; }
; #pragma unroll
;             for (int kt = 0; kt < 4; ++kt) cf[kt] = *(const bf16x8*)(Cfrag + ((size_t)(g * 4 + kt) * 64 + lane) * 8);
;             dd = *(const f32x4*)(dskip + g * 16 + 4 * fq);
;         }
;         f32x2 sv = {sr, si}; const f32x2 axx = {a.x, a.x}, ayn = {-a.y, a.y};
;         const bf16_t* zrow = z + (tok0 + fr) * DM + g * 16 + 4 * fq;
;         u32x2 ucur = *(const u32x2*)zrow;
; #pragma nounroll
;         for (int mt = 0; mt < 64; ++mt) {
;             u32x2 unext = ucur; if (mt < 63) unext = *(const u32x2*)(zrow + (size_t)(mt + 1) * 16 * DM);
;             const bf16x4 af = __builtin_bit_cast(bf16x4, ucur);
;             f32x4 d[8];
; #pragma unroll
;             for (int t = 0; t < 8; ++t) d[t] = __builtin_amdgcn_mfma_f32_16x16x16bf16_1k(af, bf[t], (f32x4){0.f, 0.f, 0.f, 0.f}, 0, 0, 0);
.LBB0_339:
	s_lshl_b32 s11, s17, 3
	s_and_b32 s19, s11, 24
	s_add_i32 s19, s19, s14
	s_lshl_b32 s12, s19, 3
	s_ashr_i32 s13, s12, 31
	s_lshl_b64 s[20:21], s[12:13], 9
	v_lshl_add_u64 v[12:13], v[4:5], 0, s[20:21]
	s_or_b32 s20, s12, 1
	s_ashr_i32 s21, s20, 31
	s_lshl_b64 s[20:21], s[20:21], 9
	v_lshl_add_u64 v[14:15], v[4:5], 0, s[20:21]
	s_or_b32 s20, s12, 2
	s_ashr_i32 s21, s20, 31
	s_lshl_b64 s[20:21], s[20:21], 9
	v_lshl_add_u64 v[16:17], v[4:5], 0, s[20:21]
	s_or_b32 s20, s12, 3
	s_ashr_i32 s21, s20, 31
	s_lshl_b64 s[20:21], s[20:21], 9
	v_lshl_add_u64 v[20:21], v[4:5], 0, s[20:21]
	s_or_b32 s20, s12, 4
	s_ashr_i32 s21, s20, 31
	s_lshl_b64 s[20:21], s[20:21], 9
	v_lshl_add_u64 v[22:23], v[4:5], 0, s[20:21]
	s_or_b32 s20, s12, 5
	s_ashr_i32 s21, s20, 31
	s_lshl_b64 s[20:21], s[20:21], 9
	v_lshl_add_u64 v[24:25], v[4:5], 0, s[20:21]
	s_or_b32 s20, s12, 6
	s_or_b32 s12, s12, 7
	s_ashr_i32 s10, s17, 4
	s_ashr_i32 s13, s12, 31
	s_bfe_u32 s18, s17, 0x20002
	s_ashr_i32 s11, s10, 31
	s_lshl_b64 s[12:13], s[12:13], 9
	s_lshl_b32 s22, s18, 10
	v_lshl_add_u64 v[18:19], v[4:5], 0, s[12:13]
	s_lshl_b64 s[12:13], s[10:11], 12
	s_ashr_i32 s21, s20, 31
	s_or_b32 s11, s12, s22
	v_lshl_or_b32 v10, s19, 7, v1
	s_lshl_b64 s[20:21], s[20:21], 9
	v_mov_b32_e32 v29, s13
	v_or_b32_e32 v28, s11, v0
	v_ashrrev_i32_e32 v11, 31, v10
	v_lshl_add_u64 v[26:27], v[4:5], 0, s[20:21]
	v_lshlrev_b64 v[28:29], 11, v[28:29]
	s_lshl_b32 s20, s19, 4
	v_lshl_add_u64 v[10:11], v[10:11], 2, s[0:1]
	v_lshl_add_u64 v[28:29], s[94:95], 0, v[28:29]
	s_ashr_i32 s21, s20, 31
	global_load_dwordx2 v[10:11], v[10:11], off
	s_nop 0
	s_nop 0
	s_nop 0
	v_lshl_add_u64 v[28:29], s[20:21], 1, v[28:29]
	v_lshl_add_u64 v[28:29], v[28:29], 0, v[168:169]
	s_nop 0
	global_load_dwordx2 v[36:37], v[28:29], off
	s_nop 0
	s_nop 0
	s_nop 0
	s_nop 0
	v_and_b32_e32 v72, 48, v162
	v_lshlrev_b32_e32 v72, 3, v72
	v_mov_b32_e32 v73, 0
	v_lshl_add_u64 v[70:71], v[12:13], 0, v[72:73]
	global_load_dwordx2 v[12:13], v[70:71], off
	global_load_dwordx2 v[14:15], v[70:71], off offset:128
	global_load_dwordx2 v[16:17], v[70:71], off offset:1024
	global_load_dwordx2 v[18:19], v[70:71], off offset:1152
	global_load_dwordx2 v[20:21], v[70:71], off offset:2048
	global_load_dwordx2 v[22:23], v[70:71], off offset:2176
	global_load_dwordx2 v[24:25], v[70:71], off offset:3072
	global_load_dwordx2 v[26:27], v[70:71], off offset:3200
	v_lshlrev_b32_e32 v28, 4, v3
	v_and_b32_e32 v28, 0x180, v28
	v_or_b32_e32 v30, s12, v0
	v_add_u32_e32 v28, s16, v28
	v_mov_b32_e32 v31, s13
	v_or_b32_e32 v30, s22, v30
	v_ashrrev_i32_e32 v29, 31, v28
	v_lshlrev_b64 v[30:31], 11, v[30:31]
	v_lshl_add_u64 v[28:29], v[28:29], 1, v[30:31]
	v_mov_b32_e32 v34, 0
	v_lshl_add_u64 v[28:29], v[8:9], 0, v[28:29]
	s_mov_b64 s[12:13], 0
	v_mov_b32_e32 v35, v34
	s_waitcnt vmcnt(0)
	v_mov_b32_e32 v30, v10
	v_mov_b32_e32 v31, v10
	v_xor_b32_e32 v10, 0x80000000, v11
	v_mov_b64_e32 v[32:33], v[36:37]
	v_and_b32_e32 v70, 48, v208
	v_lshrrev_b32_e32 v70, 1, v70
	v_lshl_add_u32 v71, v0, 5, s15
	v_add_u32_e32 v146, v71, v70
	v_lshrrev_b32_e32 v70, 5, v208
	v_lshrrev_b32_e32 v71, 2, v208
	v_xor_b32_e32 v70, v70, v71
	v_and_b32_e32 v70, 1, v70
	v_bfe_u32 v71, v208, 3, 1
	v_or_b32_e32 v72, v70, v71
	v_xor_b32_e32 v71, 1, v71
	v_or_b32_e32 v73, v70, v71
	v_and_b32_e32 v70, 3, v208
	v_lshl_add_u32 v70, v70, 5, s15
	v_and_b32_e32 v71, 16, v208
	v_add_u32_e32 v70, v70, v71
	v_mov_b32_e32 v71, s15
	v_add_u32_e32 v71, 0x200, v71
	v_cmp_eq_u32_e32 vcc, 0, v72
	s_nop 1
	v_cndmask_b32_e32 v196, v71, v70, vcc
	v_cmp_eq_u32_e32 vcc, 0, v73
	s_nop 1
	v_cndmask_b32_e32 v197, v71, v70, vcc
	v_mov_b32_e32 v72, 0
	v_mov_b32_e32 v73, 0
	v_mov_b32_e32 v74, 0
	v_mov_b32_e32 v75, 0
	v_lshl_add_u32 v70, v208, 4, s15
	ds_write_b128 v70, v[72:75] offset:512
	v_mov_b64_e32 v[54:55], v[28:29]
	s_lshl_b32 s22, s2, 26
	s_mov_b32 s23, 0
	v_lshl_add_u64 v[56:57], v[172:173], 0, s[22:23]
	v_readlane_b32 s22, v253, 8
	v_readlane_b32 s23, v253, 9
	s_nop 1
	v_lshl_add_u64 v[58:59], s[22:23], 0, v[170:171]
	ds_write_b64 v146, v[36:37]
	ds_read_b128 v[156:159], v196 offset:0
	ds_read_b128 v[200:203], v197 offset:0
	ds_read_b128 v[204:207], v196 offset:128
	ds_read_b128 v[212:215], v197 offset:128
	s_mov_b64 s[20:21], 0x8000
	global_load_dwordx2 v[40:41], v[54:55], off
	global_load_dwordx2 v[144:145], v[54:55], off
	v_lshl_add_u64 v[54:55], v[54:55], 0, s[20:21]
	global_load_dwordx2 v[42:43], v[54:55], off
	global_load_dwordx2 v[144:145], v[54:55], off
	v_lshl_add_u64 v[54:55], v[54:55], 0, s[20:21]
	global_load_dwordx2 v[44:45], v[54:55], off
	global_load_dwordx2 v[144:145], v[54:55], off
	v_lshl_add_u64 v[54:55], v[54:55], 0, s[20:21]
	global_load_dwordx2 v[46:47], v[54:55], off
	global_load_dwordx2 v[144:145], v[54:55], off
	v_lshl_add_u64 v[54:55], v[54:55], 0, s[20:21]
	global_load_dwordx2 v[48:49], v[54:55], off
	global_load_dwordx2 v[144:145], v[54:55], off
	v_lshl_add_u64 v[54:55], v[54:55], 0, s[20:21]
	s_waitcnt lgkmcnt(0)
	v_mfma_f32_16x16x32_bf16 v[88:91], v[156:159], v[12:15], 0
	v_mfma_f32_16x16x32_bf16 v[92:95], v[156:159], v[20:23], 0
	v_mfma_f32_16x16x32_bf16 v[88:91], v[200:203], v[16:19], v[88:91]
	v_mfma_f32_16x16x32_bf16 v[92:95], v[200:203], v[24:27], v[92:95]
	v_mfma_f32_16x16x32_bf16 v[96:99], v[204:207], v[12:15], 0
	v_mfma_f32_16x16x32_bf16 v[100:103], v[204:207], v[20:23], 0
	v_mfma_f32_16x16x32_bf16 v[96:99], v[212:215], v[16:19], v[96:99]
	v_mfma_f32_16x16x32_bf16 v[100:103], v[212:215], v[24:27], v[100:103]
	ds_read_b128 v[156:159], v196 offset:256
	ds_read_b128 v[200:203], v197 offset:256
	ds_read_b128 v[204:207], v196 offset:384
	ds_read_b128 v[212:215], v197 offset:384
	s_waitcnt lgkmcnt(0)
	v_mfma_f32_16x16x32_bf16 v[104:107], v[156:159], v[12:15], 0
	v_mfma_f32_16x16x32_bf16 v[108:111], v[156:159], v[20:23], 0
	v_mfma_f32_16x16x32_bf16 v[104:107], v[200:203], v[16:19], v[104:107]
	v_mfma_f32_16x16x32_bf16 v[108:111], v[200:203], v[24:27], v[108:111]
	v_mfma_f32_16x16x32_bf16 v[112:115], v[204:207], v[12:15], 0
	v_mfma_f32_16x16x32_bf16 v[116:119], v[204:207], v[20:23], 0
	v_mfma_f32_16x16x32_bf16 v[112:115], v[212:215], v[16:19], v[112:115]
	v_mfma_f32_16x16x32_bf16 v[116:119], v[212:215], v[24:27], v[116:119]
	s_mov_b32 s12, 0
; #define LAS __attribute__((address_space(3)))
; __device__ __forceinline__ unsigned cvt_pk_bf16(float lo, float hi) { const f32x2 v = {lo, hi}; return __builtin_bit_cast(unsigned, __builtin_convertvector(v, bfx2_t)); }
; __device__ __forceinline__ void conv_p(const Params& P, int l) {
;     ...
;     for (; i + 3 * stride < n8; i += 4 * stride) {
;         f32x4 a[4], b[4];
; #pragma unroll
;         for (int q = 0; q < 4; ++q) { a[q] = *(const f32x4*)(src + (i + q * stride) * 8); b[q] = *(const f32x4*)(src + (i + q * stride) * 8 + 4); }
; #pragma unroll
;         for (int q = 0; q < 4; ++q) { u32x4 w; w.x = cvt_pk_bf16(a[q][0], a[q][1]); w.y = cvt_pk_bf16(a[q][2], a[q][3]); w.z = cvt_pk_bf16(b[q][0], b[q][1]); w.w = cvt_pk_bf16(b[q][2], b[q][3]);
;             *(u32x4*)(dst + (i + q * stride) * 8) = w; }
; template <int PASS> __device__ void ssm_pass(const Params& P, int l, LAS unsigned char* lds) {
;     ...
;         for (int mt = 0; mt < 64; ++mt) {
;             u32x2 unext = ucur; if (mt < 63) unext = *(const u32x2*)(zrow + (size_t)(mt + 1) * 16 * DM);
;             const bf16x4 af = __builtin_bit_cast(bf16x4, ucur);
;             f32x4 d[8];
; #pragma unroll
;             for (int t = 0; t < 8; ++t) d[t] = __builtin_amdgcn_mfma_f32_16x16x16bf16_1k(af, bf[t], (f32x4){0.f, 0.f, 0.f, 0.f}, 0, 0, 0);
; #pragma unroll
;             for (int tq = 0; tq < 4; ++tq)
; #pragma unroll
;                 for (int j = 0; j < 4; ++j) *(LAS f32x2*)(BU + (4 * fq + j) * 528 + (16 * tq + fr) * 8) = (f32x2){d[tq][j], d[tq + 4][j]};
;             asm volatile("s_waitcnt lgkmcnt(0)" ::: "memory");
; #pragma unroll
;             for (int j = 0; j < 16; ++j) {
;                 const f32x2 bu = *(const LAS f32x2*)(BU + j * 528 + lane * 8);
;                 sv = __builtin_elementwise_fma(ayn, __builtin_shufflevector(sv, sv, 1, 0), __builtin_elementwise_fma(axx, sv, bu));
;                 if (PASS == 2) *(LAS unsigned*)(SI + j * 272 + lane * 4) = cvt_pk_bf16(sv.x, sv.y);
;             }
.Lp1_loop:
	s_waitcnt vmcnt(9)
	ds_write_b64 v146, v[40:41]
	ds_read_b128 v[156:159], v196 offset:0
	ds_read_b128 v[200:203], v197 offset:0
	ds_read_b128 v[204:207], v196 offset:128
	ds_read_b128 v[212:215], v197 offset:128
	global_load_dwordx2 v[50:51], v[54:55], off
	v_lshl_add_u64 v[54:55], v[54:55], 0, s[20:21]
	global_load_dwordx4 v[60:63], v[56:57], off
	v_fma_f32 v70, v30, v34, v88
	v_fma_f32 v71, v30, v35, v92
	v_fma_f32 v72, v10, v35, v70
	v_fma_f32 v73, v11, v34, v71
	v_fma_f32 v70, v30, v72, v89
	v_fma_f32 v71, v30, v73, v93
	v_fma_f32 v34, v10, v73, v70
	v_fma_f32 v35, v11, v72, v71
	v_fma_f32 v70, v30, v34, v90
	v_fma_f32 v71, v30, v35, v94
	v_fma_f32 v72, v10, v35, v70
	v_fma_f32 v73, v11, v34, v71
	v_fma_f32 v70, v30, v72, v91
	v_fma_f32 v71, v30, v73, v95
	v_fma_f32 v34, v10, v73, v70
	v_fma_f32 v35, v11, v72, v71
	s_waitcnt lgkmcnt(0)
	v_mfma_f32_16x16x32_bf16 v[120:123], v[156:159], v[12:15], 0
	v_mfma_f32_16x16x32_bf16 v[124:127], v[156:159], v[20:23], 0
	v_mfma_f32_16x16x32_bf16 v[120:123], v[200:203], v[16:19], v[120:123]
	v_mfma_f32_16x16x32_bf16 v[124:127], v[200:203], v[24:27], v[124:127]
	v_fma_f32 v70, v30, v34, v96
	v_fma_f32 v71, v30, v35, v100
	v_fma_f32 v72, v10, v35, v70
	v_fma_f32 v73, v11, v34, v71
	v_fma_f32 v70, v30, v72, v97
	v_fma_f32 v71, v30, v73, v101
	v_fma_f32 v34, v10, v73, v70
	v_fma_f32 v35, v11, v72, v71
	v_mfma_f32_16x16x32_bf16 v[128:131], v[204:207], v[12:15], 0
	v_mfma_f32_16x16x32_bf16 v[132:135], v[204:207], v[20:23], 0
	v_mfma_f32_16x16x32_bf16 v[128:131], v[212:215], v[16:19], v[128:131]
	v_mfma_f32_16x16x32_bf16 v[132:135], v[212:215], v[24:27], v[132:135]
	ds_read_b128 v[156:159], v196 offset:256
	ds_read_b128 v[200:203], v197 offset:256
	ds_read_b128 v[204:207], v196 offset:384
	ds_read_b128 v[212:215], v197 offset:384
	v_fma_f32 v70, v30, v34, v98
	v_fma_f32 v71, v30, v35, v102
	v_fma_f32 v72, v10, v35, v70
	v_fma_f32 v73, v11, v34, v71
	v_fma_f32 v70, v30, v72, v99
	v_fma_f32 v71, v30, v73, v103
	v_fma_f32 v34, v10, v73, v70
	v_fma_f32 v35, v11, v72, v71
	v_fma_f32 v70, v30, v34, v104
	v_fma_f32 v71, v30, v35, v108
	v_fma_f32 v72, v10, v35, v70
	v_fma_f32 v73, v11, v34, v71
	v_fma_f32 v70, v30, v72, v105
	v_fma_f32 v71, v30, v73, v109
	v_fma_f32 v34, v10, v73, v70
	v_fma_f32 v35, v11, v72, v71
	s_waitcnt lgkmcnt(0)
	v_mfma_f32_16x16x32_bf16 v[136:139], v[156:159], v[12:15], 0
	v_mfma_f32_16x16x32_bf16 v[140:143], v[156:159], v[20:23], 0
	v_mfma_f32_16x16x32_bf16 v[136:139], v[200:203], v[16:19], v[136:139]
	v_mfma_f32_16x16x32_bf16 v[140:143], v[200:203], v[24:27], v[140:143]
	v_fma_f32 v70, v30, v34, v106
	v_fma_f32 v71, v30, v35, v110
	v_fma_f32 v72, v10, v35, v70
	v_fma_f32 v73, v11, v34, v71
	v_fma_f32 v70, v30, v72, v107
	v_fma_f32 v71, v30, v73, v111
	v_fma_f32 v34, v10, v73, v70
	v_fma_f32 v35, v11, v72, v71
	v_mfma_f32_16x16x32_bf16 v[148:151], v[204:207], v[12:15], 0
	v_mfma_f32_16x16x32_bf16 v[152:155], v[204:207], v[20:23], 0
	v_mfma_f32_16x16x32_bf16 v[148:151], v[212:215], v[16:19], v[148:151]
	v_mfma_f32_16x16x32_bf16 v[152:155], v[212:215], v[24:27], v[152:155]
	v_fma_f32 v70, v30, v34, v112
	v_fma_f32 v71, v30, v35, v116
	v_fma_f32 v72, v10, v35, v70
	v_fma_f32 v73, v11, v34, v71
	v_fma_f32 v70, v30, v72, v113
	v_fma_f32 v71, v30, v73, v117
	v_fma_f32 v34, v10, v73, v70
	v_fma_f32 v35, v11, v72, v71
	v_fma_f32 v70, v30, v34, v114
	v_fma_f32 v71, v30, v35, v118
	v_fma_f32 v72, v10, v35, v70
	v_fma_f32 v73, v11, v34, v71
	v_fma_f32 v70, v30, v72, v115
	v_fma_f32 v71, v30, v73, v119
	v_fma_f32 v34, v10, v73, v70
	v_fma_f32 v35, v11, v72, v71
	s_waitcnt vmcnt(9)
	ds_write_b64 v146, v[42:43]
	ds_read_b128 v[156:159], v196 offset:0
	ds_read_b128 v[200:203], v197 offset:0
	ds_read_b128 v[204:207], v196 offset:128
	ds_read_b128 v[212:215], v197 offset:128
	global_load_dwordx2 v[52:53], v[54:55], off
	v_lshl_add_u64 v[54:55], v[54:55], 0, s[20:21]
	global_load_dwordx4 v[64:67], v[56:57], off offset:16
	s_mov_b64 s[22:23], 0x400000
	v_lshl_add_u64 v[56:57], v[56:57], 0, s[22:23]
	v_fma_f32 v70, v30, v34, v120
	v_fma_f32 v71, v30, v35, v124
	v_fma_f32 v72, v10, v35, v70
	v_fma_f32 v73, v11, v34, v71
	v_fma_f32 v70, v30, v72, v121
	v_fma_f32 v71, v30, v73, v125
	v_fma_f32 v34, v10, v73, v70
	v_fma_f32 v35, v11, v72, v71
	v_fma_f32 v70, v30, v34, v122
	v_fma_f32 v71, v30, v35, v126
	v_fma_f32 v72, v10, v35, v70
	v_fma_f32 v73, v11, v34, v71
	v_fma_f32 v70, v30, v72, v123
	v_fma_f32 v71, v30, v73, v127
	v_fma_f32 v34, v10, v73, v70
	v_fma_f32 v35, v11, v72, v71
	s_waitcnt lgkmcnt(0)
	v_mfma_f32_16x16x32_bf16 v[88:91], v[156:159], v[12:15], 0
	v_mfma_f32_16x16x32_bf16 v[92:95], v[156:159], v[20:23], 0
	v_mfma_f32_16x16x32_bf16 v[88:91], v[200:203], v[16:19], v[88:91]
	v_mfma_f32_16x16x32_bf16 v[92:95], v[200:203], v[24:27], v[92:95]
	v_fma_f32 v70, v30, v34, v128
	v_fma_f32 v71, v30, v35, v132
	v_fma_f32 v72, v10, v35, v70
	v_fma_f32 v73, v11, v34, v71
	v_fma_f32 v70, v30, v72, v129
	v_fma_f32 v71, v30, v73, v133
	v_fma_f32 v34, v10, v73, v70
	v_fma_f32 v35, v11, v72, v71
	v_mfma_f32_16x16x32_bf16 v[96:99], v[204:207], v[12:15], 0
	v_mfma_f32_16x16x32_bf16 v[100:103], v[204:207], v[20:23], 0
	v_mfma_f32_16x16x32_bf16 v[96:99], v[212:215], v[16:19], v[96:99]
	v_mfma_f32_16x16x32_bf16 v[100:103], v[212:215], v[24:27], v[100:103]
	ds_read_b128 v[156:159], v196 offset:256
	ds_read_b128 v[200:203], v197 offset:256
	ds_read_b128 v[204:207], v196 offset:384
	ds_read_b128 v[212:215], v197 offset:384
	v_fma_f32 v70, v30, v34, v130
	v_fma_f32 v71, v30, v35, v134
	v_fma_f32 v72, v10, v35, v70
	v_fma_f32 v73, v11, v34, v71
	v_fma_f32 v70, v30, v72, v131
	v_fma_f32 v71, v30, v73, v135
	v_fma_f32 v34, v10, v73, v70
	v_fma_f32 v35, v11, v72, v71
	v_fma_f32 v70, v30, v34, v136
	v_fma_f32 v71, v30, v35, v140
	v_fma_f32 v72, v10, v35, v70
	v_fma_f32 v73, v11, v34, v71
	v_fma_f32 v70, v30, v72, v137
	v_fma_f32 v71, v30, v73, v141
	v_fma_f32 v34, v10, v73, v70
	v_fma_f32 v35, v11, v72, v71
	s_waitcnt lgkmcnt(0)
; #define LAS __attribute__((address_space(3)))
; __device__ __forceinline__ unsigned cvt_pk_bf16(float lo, float hi) { const f32x2 v = {lo, hi}; return __builtin_bit_cast(unsigned, __builtin_convertvector(v, bfx2_t)); }
; __device__ __forceinline__ void conv_p(const Params& P, int l) {
;     ...
;     for (; i + 3 * stride < n8; i += 4 * stride) {
;         f32x4 a[4], b[4];
; #pragma unroll
;         for (int q = 0; q < 4; ++q) { a[q] = *(const f32x4*)(src + (i + q * stride) * 8); b[q] = *(const f32x4*)(src + (i + q * stride) * 8 + 4); }
; #pragma unroll
;         for (int q = 0; q < 4; ++q) { u32x4 w; w.x = cvt_pk_bf16(a[q][0], a[q][1]); w.y = cvt_pk_bf16(a[q][2], a[q][3]); w.z = cvt_pk_bf16(b[q][0], b[q][1]); w.w = cvt_pk_bf16(b[q][2], b[q][3]);
;             *(u32x4*)(dst + (i + q * stride) * 8) = w; }
; template <int PASS> __device__ void ssm_pass(const Params& P, int l, LAS unsigned char* lds) {
;     ...
;         for (int mt = 0; mt < 64; ++mt) {
;             u32x2 unext = ucur; if (mt < 63) unext = *(const u32x2*)(zrow + (size_t)(mt + 1) * 16 * DM);
;             const bf16x4 af = __builtin_bit_cast(bf16x4, ucur);
;             f32x4 d[8];
; #pragma unroll
;             for (int t = 0; t < 8; ++t) d[t] = __builtin_amdgcn_mfma_f32_16x16x16bf16_1k(af, bf[t], (f32x4){0.f, 0.f, 0.f, 0.f}, 0, 0, 0);
; #pragma unroll
;             for (int tq = 0; tq < 4; ++tq)
; #pragma unroll
;                 for (int j = 0; j < 4; ++j) *(LAS f32x2*)(BU + (4 * fq + j) * 528 + (16 * tq + fr) * 8) = (f32x2){d[tq][j], d[tq + 4][j]};
;             asm volatile("s_waitcnt lgkmcnt(0)" ::: "memory");
; #pragma unroll
;             for (int j = 0; j < 16; ++j) {
;                 const f32x2 bu = *(const LAS f32x2*)(BU + j * 528 + lane * 8);
;                 sv = __builtin_elementwise_fma(ayn, __builtin_shufflevector(sv, sv, 1, 0), __builtin_elementwise_fma(axx, sv, bu));
;                 if (PASS == 2) *(LAS unsigned*)(SI + j * 272 + lane * 4) = cvt_pk_bf16(sv.x, sv.y);
;             }
	v_mfma_f32_16x16x32_bf16 v[104:107], v[156:159], v[12:15], 0
	v_mfma_f32_16x16x32_bf16 v[108:111], v[156:159], v[20:23], 0
	v_mfma_f32_16x16x32_bf16 v[104:107], v[200:203], v[16:19], v[104:107]
	v_mfma_f32_16x16x32_bf16 v[108:111], v[200:203], v[24:27], v[108:111]
	v_fma_f32 v70, v30, v34, v138
	v_fma_f32 v71, v30, v35, v142
	v_fma_f32 v72, v10, v35, v70
	v_fma_f32 v73, v11, v34, v71
	v_fma_f32 v70, v30, v72, v139
	v_fma_f32 v71, v30, v73, v143
	v_fma_f32 v34, v10, v73, v70
	v_fma_f32 v35, v11, v72, v71
	v_mfma_f32_16x16x32_bf16 v[112:115], v[204:207], v[12:15], 0
	v_mfma_f32_16x16x32_bf16 v[116:119], v[204:207], v[20:23], 0
	v_mfma_f32_16x16x32_bf16 v[112:115], v[212:215], v[16:19], v[112:115]
	v_mfma_f32_16x16x32_bf16 v[116:119], v[212:215], v[24:27], v[116:119]
	v_fma_f32 v70, v30, v34, v148
	v_fma_f32 v71, v30, v35, v152
	v_fma_f32 v72, v10, v35, v70
	v_fma_f32 v73, v11, v34, v71
	v_fma_f32 v70, v30, v72, v149
	v_fma_f32 v71, v30, v73, v153
	v_fma_f32 v34, v10, v73, v70
	v_fma_f32 v35, v11, v72, v71
	v_fma_f32 v70, v30, v34, v150
	v_fma_f32 v71, v30, v35, v154
	v_fma_f32 v72, v10, v35, v70
	v_fma_f32 v73, v11, v34, v71
	v_fma_f32 v70, v30, v72, v151
	v_fma_f32 v71, v30, v73, v155
	v_fma_f32 v34, v10, v73, v70
	v_fma_f32 v35, v11, v72, v71
	s_waitcnt vmcnt(9)
	ds_write_b64 v146, v[44:45]
	ds_read_b128 v[156:159], v196 offset:0
	ds_read_b128 v[200:203], v197 offset:0
	ds_read_b128 v[204:207], v196 offset:128
	ds_read_b128 v[212:215], v197 offset:128
	global_load_dwordx2 v[36:37], v[54:55], off
	v_lshl_add_u64 v[54:55], v[54:55], 0, s[20:21]
	global_load_dwordx2 v[144:145], v[54:55], off
	v_fma_f32 v70, v30, v34, v88
	v_fma_f32 v71, v30, v35, v92
	v_fma_f32 v72, v10, v35, v70
	v_fma_f32 v73, v11, v34, v71
	v_fma_f32 v70, v30, v72, v89
	v_fma_f32 v71, v30, v73, v93
	v_fma_f32 v34, v10, v73, v70
	v_fma_f32 v35, v11, v72, v71
	v_fma_f32 v70, v30, v34, v90
	v_fma_f32 v71, v30, v35, v94
	v_fma_f32 v72, v10, v35, v70
	v_fma_f32 v73, v11, v34, v71
	v_fma_f32 v70, v30, v72, v91
	v_fma_f32 v71, v30, v73, v95
	v_fma_f32 v34, v10, v73, v70
	v_fma_f32 v35, v11, v72, v71
	s_waitcnt lgkmcnt(0)
	v_mfma_f32_16x16x32_bf16 v[120:123], v[156:159], v[12:15], 0
	v_mfma_f32_16x16x32_bf16 v[124:127], v[156:159], v[20:23], 0
	v_mfma_f32_16x16x32_bf16 v[120:123], v[200:203], v[16:19], v[120:123]
	v_mfma_f32_16x16x32_bf16 v[124:127], v[200:203], v[24:27], v[124:127]
	v_fma_f32 v70, v30, v34, v96
	v_fma_f32 v71, v30, v35, v100
	v_fma_f32 v72, v10, v35, v70
	v_fma_f32 v73, v11, v34, v71
	v_fma_f32 v70, v30, v72, v97
	v_fma_f32 v71, v30, v73, v101
	v_fma_f32 v34, v10, v73, v70
	v_fma_f32 v35, v11, v72, v71
	v_mfma_f32_16x16x32_bf16 v[128:131], v[204:207], v[12:15], 0
	v_mfma_f32_16x16x32_bf16 v[132:135], v[204:207], v[20:23], 0
	v_mfma_f32_16x16x32_bf16 v[128:131], v[212:215], v[16:19], v[128:131]
	v_mfma_f32_16x16x32_bf16 v[132:135], v[212:215], v[24:27], v[132:135]
	ds_read_b128 v[156:159], v196 offset:256
	ds_read_b128 v[200:203], v197 offset:256
	ds_read_b128 v[204:207], v196 offset:384
	ds_read_b128 v[212:215], v197 offset:384
	v_fma_f32 v70, v30, v34, v98
	v_fma_f32 v71, v30, v35, v102
	v_fma_f32 v72, v10, v35, v70
	v_fma_f32 v73, v11, v34, v71
	v_fma_f32 v70, v30, v72, v99
	v_fma_f32 v71, v30, v73, v103
	v_fma_f32 v34, v10, v73, v70
	v_fma_f32 v35, v11, v72, v71
	v_fma_f32 v70, v30, v34, v104
	v_fma_f32 v71, v30, v35, v108
	v_fma_f32 v72, v10, v35, v70
	v_fma_f32 v73, v11, v34, v71
	v_fma_f32 v70, v30, v72, v105
	v_fma_f32 v71, v30, v73, v109
	v_fma_f32 v34, v10, v73, v70
	v_fma_f32 v35, v11, v72, v71
	s_waitcnt lgkmcnt(0)
	v_mfma_f32_16x16x32_bf16 v[136:139], v[156:159], v[12:15], 0
	v_mfma_f32_16x16x32_bf16 v[140:143], v[156:159], v[20:23], 0
	v_mfma_f32_16x16x32_bf16 v[136:139], v[200:203], v[16:19], v[136:139]
	v_mfma_f32_16x16x32_bf16 v[140:143], v[200:203], v[24:27], v[140:143]
	v_fma_f32 v70, v30, v34, v106
	v_fma_f32 v71, v30, v35, v110
	v_fma_f32 v72, v10, v35, v70
	v_fma_f32 v73, v11, v34, v71
	v_fma_f32 v70, v30, v72, v107
	v_fma_f32 v71, v30, v73, v111
	v_fma_f32 v34, v10, v73, v70
	v_fma_f32 v35, v11, v72, v71
	v_mfma_f32_16x16x32_bf16 v[148:151], v[204:207], v[12:15], 0
	v_mfma_f32_16x16x32_bf16 v[152:155], v[204:207], v[20:23], 0
	v_mfma_f32_16x16x32_bf16 v[148:151], v[212:215], v[16:19], v[148:151]
	v_mfma_f32_16x16x32_bf16 v[152:155], v[212:215], v[24:27], v[152:155]
	v_fma_f32 v70, v30, v34, v112
	v_fma_f32 v71, v30, v35, v116
	v_fma_f32 v72, v10, v35, v70
	v_fma_f32 v73, v11, v34, v71
	v_fma_f32 v70, v30, v72, v113
	v_fma_f32 v71, v30, v73, v117
	v_fma_f32 v34, v10, v73, v70
	v_fma_f32 v35, v11, v72, v71
	v_fma_f32 v70, v30, v34, v114
	v_fma_f32 v71, v30, v35, v118
	v_fma_f32 v72, v10, v35, v70
	v_fma_f32 v73, v11, v34, v71
	v_fma_f32 v70, v30, v72, v115
	v_fma_f32 v71, v30, v73, v119
	v_fma_f32 v34, v10, v73, v70
	v_fma_f32 v35, v11, v72, v71
	s_waitcnt vmcnt(9)
	ds_write_b64 v146, v[46:47]
	ds_read_b128 v[156:159], v196 offset:0
	ds_read_b128 v[200:203], v197 offset:0
	ds_read_b128 v[204:207], v196 offset:128
	ds_read_b128 v[212:215], v197 offset:128
	global_load_dwordx2 v[40:41], v[54:55], off
	v_lshl_add_u64 v[54:55], v[54:55], 0, s[20:21]
	s_cmp_eq_u32 s12, 0
	s_cbranch_scc1 .Lp1_skip
	v_cvt_pk_bf16_f32 v82, v74, v75
	v_cvt_pk_bf16_f32 v83, v76, v77
	v_cvt_pk_bf16_f32 v84, v78, v79
	v_cvt_pk_bf16_f32 v85, v80, v81
	global_store_dwordx4 v[58:59], v[82:85], off
	s_mov_b64 s[22:23], 0x200000
	v_lshl_add_u64 v[58:59], v[58:59], 0, s[22:23]
	s_branch .Lp1_join
.Lp1_skip:
	global_load_dwordx2 v[144:145], v[54:55], off
; #define LAS __attribute__((address_space(3)))
; __device__ __forceinline__ unsigned cvt_pk_bf16(float lo, float hi) { const f32x2 v = {lo, hi}; return __builtin_bit_cast(unsigned, __builtin_convertvector(v, bfx2_t)); }
; __device__ __forceinline__ void conv_p(const Params& P, int l) {
;     ...
;     for (; i + 3 * stride < n8; i += 4 * stride) {
;         f32x4 a[4], b[4];
; #pragma unroll
;         for (int q = 0; q < 4; ++q) { a[q] = *(const f32x4*)(src + (i + q * stride) * 8); b[q] = *(const f32x4*)(src + (i + q * stride) * 8 + 4); }
; #pragma unroll
;         for (int q = 0; q < 4; ++q) { u32x4 w; w.x = cvt_pk_bf16(a[q][0], a[q][1]); w.y = cvt_pk_bf16(a[q][2], a[q][3]); w.z = cvt_pk_bf16(b[q][0], b[q][1]); w.w = cvt_pk_bf16(b[q][2], b[q][3]);
;             *(u32x4*)(dst + (i + q * stride) * 8) = w; }
; template <int PASS> __device__ void ssm_pass(const Params& P, int l, LAS unsigned char* lds) {
;     ...
;         for (int mt = 0; mt < 64; ++mt) {
;             u32x2 unext = ucur; if (mt < 63) unext = *(const u32x2*)(zrow + (size_t)(mt + 1) * 16 * DM);
;             const bf16x4 af = __builtin_bit_cast(bf16x4, ucur);
;             f32x4 d[8];
; #pragma unroll
;             for (int t = 0; t < 8; ++t) d[t] = __builtin_amdgcn_mfma_f32_16x16x16bf16_1k(af, bf[t], (f32x4){0.f, 0.f, 0.f, 0.f}, 0, 0, 0);
; #pragma unroll
;             for (int tq = 0; tq < 4; ++tq)
; #pragma unroll
;                 for (int j = 0; j < 4; ++j) *(LAS f32x2*)(BU + (4 * fq + j) * 528 + (16 * tq + fr) * 8) = (f32x2){d[tq][j], d[tq + 4][j]};
;             asm volatile("s_waitcnt lgkmcnt(0)" ::: "memory");
; #pragma unroll
;             for (int j = 0; j < 16; ++j) {
;                 const f32x2 bu = *(const LAS f32x2*)(BU + j * 528 + lane * 8);
;                 sv = __builtin_elementwise_fma(ayn, __builtin_shufflevector(sv, sv, 1, 0), __builtin_elementwise_fma(axx, sv, bu));
;                 if (PASS == 2) *(LAS unsigned*)(SI + j * 272 + lane * 4) = cvt_pk_bf16(sv.x, sv.y);
;             }
.Lp1_join:
	v_fma_f32 v70, v30, v34, v120
	v_fma_f32 v71, v30, v35, v124
	v_fma_f32 v72, v10, v35, v70
	v_fma_f32 v73, v11, v34, v71
	v_fma_f32 v70, v30, v72, v121
	v_fma_f32 v71, v30, v73, v125
	v_fma_f32 v34, v10, v73, v70
	v_fma_f32 v35, v11, v72, v71
	v_fma_f32 v70, v30, v34, v122
	v_fma_f32 v71, v30, v35, v126
	v_fma_f32 v72, v10, v35, v70
	v_fma_f32 v73, v11, v34, v71
	v_fma_f32 v70, v30, v72, v123
	v_fma_f32 v71, v30, v73, v127
	v_fma_f32 v34, v10, v73, v70
	v_fma_f32 v35, v11, v72, v71
	s_waitcnt lgkmcnt(0)
	v_mfma_f32_16x16x32_bf16 v[88:91], v[156:159], v[12:15], 0
	v_mfma_f32_16x16x32_bf16 v[92:95], v[156:159], v[20:23], 0
	v_mfma_f32_16x16x32_bf16 v[88:91], v[200:203], v[16:19], v[88:91]
	v_mfma_f32_16x16x32_bf16 v[92:95], v[200:203], v[24:27], v[92:95]
	v_fma_f32 v70, v30, v34, v128
	v_fma_f32 v71, v30, v35, v132
	v_fma_f32 v72, v10, v35, v70
	v_fma_f32 v73, v11, v34, v71
	v_fma_f32 v70, v30, v72, v129
	v_fma_f32 v71, v30, v73, v133
	v_fma_f32 v34, v10, v73, v70
	v_fma_f32 v35, v11, v72, v71
	v_mfma_f32_16x16x32_bf16 v[96:99], v[204:207], v[12:15], 0
	v_mfma_f32_16x16x32_bf16 v[100:103], v[204:207], v[20:23], 0
	v_mfma_f32_16x16x32_bf16 v[96:99], v[212:215], v[16:19], v[96:99]
	v_mfma_f32_16x16x32_bf16 v[100:103], v[212:215], v[24:27], v[100:103]
	ds_read_b128 v[156:159], v196 offset:256
	ds_read_b128 v[200:203], v197 offset:256
	ds_read_b128 v[204:207], v196 offset:384
	ds_read_b128 v[212:215], v197 offset:384
	v_fma_f32 v70, v30, v34, v130
	v_fma_f32 v71, v30, v35, v134
	v_fma_f32 v72, v10, v35, v70
	v_fma_f32 v73, v11, v34, v71
	v_fma_f32 v70, v30, v72, v131
	v_fma_f32 v71, v30, v73, v135
	v_fma_f32 v34, v10, v73, v70
	v_fma_f32 v35, v11, v72, v71
	v_fma_f32 v70, v30, v34, v136
	v_fma_f32 v71, v30, v35, v140
	v_fma_f32 v72, v10, v35, v70
	v_fma_f32 v73, v11, v34, v71
	v_fma_f32 v70, v30, v72, v137
	v_fma_f32 v71, v30, v73, v141
	v_fma_f32 v34, v10, v73, v70
	v_fma_f32 v35, v11, v72, v71
	s_waitcnt lgkmcnt(0)
	v_mfma_f32_16x16x32_bf16 v[104:107], v[156:159], v[12:15], 0
	v_mfma_f32_16x16x32_bf16 v[108:111], v[156:159], v[20:23], 0
	v_mfma_f32_16x16x32_bf16 v[104:107], v[200:203], v[16:19], v[104:107]
	v_mfma_f32_16x16x32_bf16 v[108:111], v[200:203], v[24:27], v[108:111]
	v_fma_f32 v70, v30, v34, v138
	v_fma_f32 v71, v30, v35, v142
	v_fma_f32 v72, v10, v35, v70
	v_fma_f32 v73, v11, v34, v71
	v_fma_f32 v70, v30, v72, v139
	v_fma_f32 v71, v30, v73, v143
	v_fma_f32 v34, v10, v73, v70
	v_fma_f32 v35, v11, v72, v71
	v_mfma_f32_16x16x32_bf16 v[112:115], v[204:207], v[12:15], 0
	v_mfma_f32_16x16x32_bf16 v[116:119], v[204:207], v[20:23], 0
	v_mfma_f32_16x16x32_bf16 v[112:115], v[212:215], v[16:19], v[112:115]
	v_mfma_f32_16x16x32_bf16 v[116:119], v[212:215], v[24:27], v[116:119]
	v_fma_f32 v70, v30, v34, v148
	v_fma_f32 v71, v30, v35, v152
	v_fma_f32 v72, v10, v35, v70
	v_fma_f32 v73, v11, v34, v71
	v_fma_f32 v70, v30, v72, v149
	v_fma_f32 v71, v30, v73, v153
	v_fma_f32 v34, v10, v73, v70
	v_fma_f32 v35, v11, v72, v71
	v_fma_f32 v70, v30, v34, v150
	v_fma_f32 v71, v30, v35, v154
	v_fma_f32 v72, v10, v35, v70
	v_fma_f32 v73, v11, v34, v71
	v_fma_f32 v70, v30, v72, v151
	v_fma_f32 v71, v30, v73, v155
	v_fma_f32 v34, v10, v73, v70
	v_fma_f32 v35, v11, v72, v71
	s_waitcnt vmcnt(9)
	ds_write_b64 v146, v[48:49]
	ds_read_b128 v[156:159], v196 offset:0
	ds_read_b128 v[200:203], v197 offset:0
	ds_read_b128 v[204:207], v196 offset:128
	ds_read_b128 v[212:215], v197 offset:128
	global_load_dwordx2 v[42:43], v[54:55], off
	v_lshl_add_u64 v[54:55], v[54:55], 0, s[20:21]
	global_load_dwordx4 v[74:77], v[56:57], off
	v_fma_f32 v70, v30, v34, v88
	v_fma_f32 v71, v30, v35, v92
	v_fma_f32 v72, v10, v35, v70
	v_fma_f32 v73, v11, v34, v71
	v_fma_f32 v70, v30, v72, v89
	v_fma_f32 v71, v30, v73, v93
	v_fma_f32 v34, v10, v73, v70
	v_fma_f32 v35, v11, v72, v71
	v_fma_f32 v70, v30, v34, v90
	v_fma_f32 v71, v30, v35, v94
	v_fma_f32 v72, v10, v35, v70
	v_fma_f32 v73, v11, v34, v71
	v_fma_f32 v70, v30, v72, v91
	v_fma_f32 v71, v30, v73, v95
	v_fma_f32 v34, v10, v73, v70
	v_fma_f32 v35, v11, v72, v71
	s_waitcnt lgkmcnt(0)
	v_mfma_f32_16x16x32_bf16 v[120:123], v[156:159], v[12:15], 0
	v_mfma_f32_16x16x32_bf16 v[124:127], v[156:159], v[20:23], 0
	v_mfma_f32_16x16x32_bf16 v[120:123], v[200:203], v[16:19], v[120:123]
	v_mfma_f32_16x16x32_bf16 v[124:127], v[200:203], v[24:27], v[124:127]
	v_fma_f32 v70, v30, v34, v96
	v_fma_f32 v71, v30, v35, v100
	v_fma_f32 v72, v10, v35, v70
	v_fma_f32 v73, v11, v34, v71
	v_fma_f32 v70, v30, v72, v97
	v_fma_f32 v71, v30, v73, v101
	v_fma_f32 v34, v10, v73, v70
	v_fma_f32 v35, v11, v72, v71
	v_mfma_f32_16x16x32_bf16 v[128:131], v[204:207], v[12:15], 0
	v_mfma_f32_16x16x32_bf16 v[132:135], v[204:207], v[20:23], 0
	v_mfma_f32_16x16x32_bf16 v[128:131], v[212:215], v[16:19], v[128:131]
	v_mfma_f32_16x16x32_bf16 v[132:135], v[212:215], v[24:27], v[132:135]
	ds_read_b128 v[156:159], v196 offset:256
	ds_read_b128 v[200:203], v197 offset:256
	ds_read_b128 v[204:207], v196 offset:384
	ds_read_b128 v[212:215], v197 offset:384
	v_fma_f32 v70, v30, v34, v98
	v_fma_f32 v71, v30, v35, v102
	v_fma_f32 v72, v10, v35, v70
	v_fma_f32 v73, v11, v34, v71
	v_fma_f32 v70, v30, v72, v99
	v_fma_f32 v71, v30, v73, v103
	v_fma_f32 v34, v10, v73, v70
	v_fma_f32 v35, v11, v72, v71
	v_fma_f32 v70, v30, v34, v104
	v_fma_f32 v71, v30, v35, v108
	v_fma_f32 v72, v10, v35, v70
	v_fma_f32 v73, v11, v34, v71
	v_fma_f32 v70, v30, v72, v105
	v_fma_f32 v71, v30, v73, v109
	v_fma_f32 v34, v10, v73, v70
	v_fma_f32 v35, v11, v72, v71
	s_waitcnt lgkmcnt(0)
; #define LAS __attribute__((address_space(3)))
; __device__ __forceinline__ unsigned cvt_pk_bf16(float lo, float hi) { const f32x2 v = {lo, hi}; return __builtin_bit_cast(unsigned, __builtin_convertvector(v, bfx2_t)); }
; __device__ __forceinline__ void conv_p(const Params& P, int l) {
;     ...
;     for (; i + 3 * stride < n8; i += 4 * stride) {
;         f32x4 a[4], b[4];
; #pragma unroll
;         for (int q = 0; q < 4; ++q) { a[q] = *(const f32x4*)(src + (i + q * stride) * 8); b[q] = *(const f32x4*)(src + (i + q * stride) * 8 + 4); }
; #pragma unroll
;         for (int q = 0; q < 4; ++q) { u32x4 w; w.x = cvt_pk_bf16(a[q][0], a[q][1]); w.y = cvt_pk_bf16(a[q][2], a[q][3]); w.z = cvt_pk_bf16(b[q][0], b[q][1]); w.w = cvt_pk_bf16(b[q][2], b[q][3]);
;             *(u32x4*)(dst + (i + q * stride) * 8) = w; }
; template <int PASS> __device__ void ssm_pass(const Params& P, int l, LAS unsigned char* lds) {
;     ...
;         for (int mt = 0; mt < 64; ++mt) {
;             u32x2 unext = ucur; if (mt < 63) unext = *(const u32x2*)(zrow + (size_t)(mt + 1) * 16 * DM);
;             const bf16x4 af = __builtin_bit_cast(bf16x4, ucur);
;             f32x4 d[8];
; #pragma unroll
;             for (int t = 0; t < 8; ++t) d[t] = __builtin_amdgcn_mfma_f32_16x16x16bf16_1k(af, bf[t], (f32x4){0.f, 0.f, 0.f, 0.f}, 0, 0, 0);
; #pragma unroll
;             for (int tq = 0; tq < 4; ++tq)
; #pragma unroll
;                 for (int j = 0; j < 4; ++j) *(LAS f32x2*)(BU + (4 * fq + j) * 528 + (16 * tq + fr) * 8) = (f32x2){d[tq][j], d[tq + 4][j]};
;             asm volatile("s_waitcnt lgkmcnt(0)" ::: "memory");
; #pragma unroll
;             for (int j = 0; j < 16; ++j) {
;                 const f32x2 bu = *(const LAS f32x2*)(BU + j * 528 + lane * 8);
;                 sv = __builtin_elementwise_fma(ayn, __builtin_shufflevector(sv, sv, 1, 0), __builtin_elementwise_fma(axx, sv, bu));
;                 if (PASS == 2) *(LAS unsigned*)(SI + j * 272 + lane * 4) = cvt_pk_bf16(sv.x, sv.y);
;             }
	v_mfma_f32_16x16x32_bf16 v[136:139], v[156:159], v[12:15], 0
	v_mfma_f32_16x16x32_bf16 v[140:143], v[156:159], v[20:23], 0
	v_mfma_f32_16x16x32_bf16 v[136:139], v[200:203], v[16:19], v[136:139]
	v_mfma_f32_16x16x32_bf16 v[140:143], v[200:203], v[24:27], v[140:143]
	v_fma_f32 v70, v30, v34, v106
	v_fma_f32 v71, v30, v35, v110
	v_fma_f32 v72, v10, v35, v70
	v_fma_f32 v73, v11, v34, v71
	v_fma_f32 v70, v30, v72, v107
	v_fma_f32 v71, v30, v73, v111
	v_fma_f32 v34, v10, v73, v70
	v_fma_f32 v35, v11, v72, v71
	v_mfma_f32_16x16x32_bf16 v[148:151], v[204:207], v[12:15], 0
	v_mfma_f32_16x16x32_bf16 v[152:155], v[204:207], v[20:23], 0
	v_mfma_f32_16x16x32_bf16 v[148:151], v[212:215], v[16:19], v[148:151]
	v_mfma_f32_16x16x32_bf16 v[152:155], v[212:215], v[24:27], v[152:155]
	v_fma_f32 v70, v30, v34, v112
	v_fma_f32 v71, v30, v35, v116
	v_fma_f32 v72, v10, v35, v70
	v_fma_f32 v73, v11, v34, v71
	v_fma_f32 v70, v30, v72, v113
	v_fma_f32 v71, v30, v73, v117
	v_fma_f32 v34, v10, v73, v70
	v_fma_f32 v35, v11, v72, v71
	v_fma_f32 v70, v30, v34, v114
	v_fma_f32 v71, v30, v35, v118
	v_fma_f32 v72, v10, v35, v70
	v_fma_f32 v73, v11, v34, v71
	v_fma_f32 v70, v30, v72, v115
	v_fma_f32 v71, v30, v73, v119
	v_fma_f32 v34, v10, v73, v70
	v_fma_f32 v35, v11, v72, v71
	s_waitcnt vmcnt(9)
	ds_write_b64 v146, v[50:51]
	ds_read_b128 v[156:159], v196 offset:0
	ds_read_b128 v[200:203], v197 offset:0
	ds_read_b128 v[204:207], v196 offset:128
	ds_read_b128 v[212:215], v197 offset:128
	global_load_dwordx2 v[44:45], v[54:55], off
	v_lshl_add_u64 v[54:55], v[54:55], 0, s[20:21]
	global_load_dwordx4 v[78:81], v[56:57], off offset:16
	s_mov_b64 s[22:23], 0x400000
	v_lshl_add_u64 v[56:57], v[56:57], 0, s[22:23]
	v_fma_f32 v70, v30, v34, v120
	v_fma_f32 v71, v30, v35, v124
	v_fma_f32 v72, v10, v35, v70
	v_fma_f32 v73, v11, v34, v71
	v_fma_f32 v70, v30, v72, v121
	v_fma_f32 v71, v30, v73, v125
	v_fma_f32 v34, v10, v73, v70
	v_fma_f32 v35, v11, v72, v71
	v_fma_f32 v70, v30, v34, v122
	v_fma_f32 v71, v30, v35, v126
	v_fma_f32 v72, v10, v35, v70
	v_fma_f32 v73, v11, v34, v71
	v_fma_f32 v70, v30, v72, v123
	v_fma_f32 v71, v30, v73, v127
	v_fma_f32 v34, v10, v73, v70
	v_fma_f32 v35, v11, v72, v71
	s_waitcnt lgkmcnt(0)
	v_mfma_f32_16x16x32_bf16 v[88:91], v[156:159], v[12:15], 0
	v_mfma_f32_16x16x32_bf16 v[92:95], v[156:159], v[20:23], 0
	v_mfma_f32_16x16x32_bf16 v[88:91], v[200:203], v[16:19], v[88:91]
	v_mfma_f32_16x16x32_bf16 v[92:95], v[200:203], v[24:27], v[92:95]
	v_fma_f32 v70, v30, v34, v128
	v_fma_f32 v71, v30, v35, v132
	v_fma_f32 v72, v10, v35, v70
	v_fma_f32 v73, v11, v34, v71
	v_fma_f32 v70, v30, v72, v129
	v_fma_f32 v71, v30, v73, v133
	v_fma_f32 v34, v10, v73, v70
	v_fma_f32 v35, v11, v72, v71
	v_mfma_f32_16x16x32_bf16 v[96:99], v[204:207], v[12:15], 0
	v_mfma_f32_16x16x32_bf16 v[100:103], v[204:207], v[20:23], 0
	v_mfma_f32_16x16x32_bf16 v[96:99], v[212:215], v[16:19], v[96:99]
	v_mfma_f32_16x16x32_bf16 v[100:103], v[212:215], v[24:27], v[100:103]
	ds_read_b128 v[156:159], v196 offset:256
	ds_read_b128 v[200:203], v197 offset:256
	ds_read_b128 v[204:207], v196 offset:384
	ds_read_b128 v[212:215], v197 offset:384
	v_fma_f32 v70, v30, v34, v130
	v_fma_f32 v71, v30, v35, v134
	v_fma_f32 v72, v10, v35, v70
	v_fma_f32 v73, v11, v34, v71
	v_fma_f32 v70, v30, v72, v131
	v_fma_f32 v71, v30, v73, v135
	v_fma_f32 v34, v10, v73, v70
	v_fma_f32 v35, v11, v72, v71
	v_fma_f32 v70, v30, v34, v136
	v_fma_f32 v71, v30, v35, v140
	v_fma_f32 v72, v10, v35, v70
	v_fma_f32 v73, v11, v34, v71
	v_fma_f32 v70, v30, v72, v137
	v_fma_f32 v71, v30, v73, v141
	v_fma_f32 v34, v10, v73, v70
	v_fma_f32 v35, v11, v72, v71
	s_waitcnt lgkmcnt(0)
	v_mfma_f32_16x16x32_bf16 v[104:107], v[156:159], v[12:15], 0
	v_mfma_f32_16x16x32_bf16 v[108:111], v[156:159], v[20:23], 0
	v_mfma_f32_16x16x32_bf16 v[104:107], v[200:203], v[16:19], v[104:107]
	v_mfma_f32_16x16x32_bf16 v[108:111], v[200:203], v[24:27], v[108:111]
	v_fma_f32 v70, v30, v34, v138
	v_fma_f32 v71, v30, v35, v142
	v_fma_f32 v72, v10, v35, v70
	v_fma_f32 v73, v11, v34, v71
	v_fma_f32 v70, v30, v72, v139
	v_fma_f32 v71, v30, v73, v143
	v_fma_f32 v34, v10, v73, v70
	v_fma_f32 v35, v11, v72, v71
	v_mfma_f32_16x16x32_bf16 v[112:115], v[204:207], v[12:15], 0
	v_mfma_f32_16x16x32_bf16 v[116:119], v[204:207], v[20:23], 0
	v_mfma_f32_16x16x32_bf16 v[112:115], v[212:215], v[16:19], v[112:115]
	v_mfma_f32_16x16x32_bf16 v[116:119], v[212:215], v[24:27], v[116:119]
	v_fma_f32 v70, v30, v34, v148
	v_fma_f32 v71, v30, v35, v152
	v_fma_f32 v72, v10, v35, v70
	v_fma_f32 v73, v11, v34, v71
	v_fma_f32 v70, v30, v72, v149
	v_fma_f32 v71, v30, v73, v153
	v_fma_f32 v34, v10, v73, v70
	v_fma_f32 v35, v11, v72, v71
	v_fma_f32 v70, v30, v34, v150
	v_fma_f32 v71, v30, v35, v154
	v_fma_f32 v72, v10, v35, v70
	v_fma_f32 v73, v11, v34, v71
	v_fma_f32 v70, v30, v72, v151
	v_fma_f32 v71, v30, v73, v155
	v_fma_f32 v34, v10, v73, v70
	v_fma_f32 v35, v11, v72, v71
	s_waitcnt vmcnt(9)
	ds_write_b64 v146, v[52:53]
	ds_read_b128 v[156:159], v196 offset:0
	ds_read_b128 v[200:203], v197 offset:0
	ds_read_b128 v[204:207], v196 offset:128
	ds_read_b128 v[212:215], v197 offset:128
	global_load_dwordx2 v[46:47], v[54:55], off
	v_lshl_add_u64 v[54:55], v[54:55], 0, s[20:21]
	global_load_dwordx2 v[144:145], v[54:55], off
	v_fma_f32 v70, v30, v34, v88
	v_fma_f32 v71, v30, v35, v92
	v_fma_f32 v72, v10, v35, v70
	v_fma_f32 v73, v11, v34, v71
	v_fma_f32 v70, v30, v72, v89
	v_fma_f32 v71, v30, v73, v93
	v_fma_f32 v34, v10, v73, v70
	v_fma_f32 v35, v11, v72, v71
	v_fma_f32 v70, v30, v34, v90
	v_fma_f32 v71, v30, v35, v94
	v_fma_f32 v72, v10, v35, v70
	v_fma_f32 v73, v11, v34, v71
	v_fma_f32 v70, v30, v72, v91
	v_fma_f32 v71, v30, v73, v95
	v_fma_f32 v34, v10, v73, v70
	v_fma_f32 v35, v11, v72, v71
	s_waitcnt lgkmcnt(0)
; #define LAS __attribute__((address_space(3)))
; __device__ __forceinline__ unsigned cvt_pk_bf16(float lo, float hi) { const f32x2 v = {lo, hi}; return __builtin_bit_cast(unsigned, __builtin_convertvector(v, bfx2_t)); }
; __device__ __forceinline__ void conv_p(const Params& P, int l) {
;     ...
;     for (; i + 3 * stride < n8; i += 4 * stride) {
;         f32x4 a[4], b[4];
; #pragma unroll
;         for (int q = 0; q < 4; ++q) { a[q] = *(const f32x4*)(src + (i + q * stride) * 8); b[q] = *(const f32x4*)(src + (i + q * stride) * 8 + 4); }
; #pragma unroll
;         for (int q = 0; q < 4; ++q) { u32x4 w; w.x = cvt_pk_bf16(a[q][0], a[q][1]); w.y = cvt_pk_bf16(a[q][2], a[q][3]); w.z = cvt_pk_bf16(b[q][0], b[q][1]); w.w = cvt_pk_bf16(b[q][2], b[q][3]);
;             *(u32x4*)(dst + (i + q * stride) * 8) = w; }
; template <int PASS> __device__ void ssm_pass(const Params& P, int l, LAS unsigned char* lds) {
;     ...
;         for (int mt = 0; mt < 64; ++mt) {
;             u32x2 unext = ucur; if (mt < 63) unext = *(const u32x2*)(zrow + (size_t)(mt + 1) * 16 * DM);
;             const bf16x4 af = __builtin_bit_cast(bf16x4, ucur);
;             f32x4 d[8];
; #pragma unroll
;             for (int t = 0; t < 8; ++t) d[t] = __builtin_amdgcn_mfma_f32_16x16x16bf16_1k(af, bf[t], (f32x4){0.f, 0.f, 0.f, 0.f}, 0, 0, 0);
; #pragma unroll
;             for (int tq = 0; tq < 4; ++tq)
; #pragma unroll
;                 for (int j = 0; j < 4; ++j) *(LAS f32x2*)(BU + (4 * fq + j) * 528 + (16 * tq + fr) * 8) = (f32x2){d[tq][j], d[tq + 4][j]};
;             asm volatile("s_waitcnt lgkmcnt(0)" ::: "memory");
; #pragma unroll
;             for (int j = 0; j < 16; ++j) {
;                 const f32x2 bu = *(const LAS f32x2*)(BU + j * 528 + lane * 8);
;                 sv = __builtin_elementwise_fma(ayn, __builtin_shufflevector(sv, sv, 1, 0), __builtin_elementwise_fma(axx, sv, bu));
;                 if (PASS == 2) *(LAS unsigned*)(SI + j * 272 + lane * 4) = cvt_pk_bf16(sv.x, sv.y);
;             }
;     ...
;         if (PASS == 1) *(f32x2*)(E + ((size_t)((b * 32 + g) * 4 + r) * 64 + lane) * 2) = sv;
	v_mfma_f32_16x16x32_bf16 v[120:123], v[156:159], v[12:15], 0
	v_mfma_f32_16x16x32_bf16 v[124:127], v[156:159], v[20:23], 0
	v_mfma_f32_16x16x32_bf16 v[120:123], v[200:203], v[16:19], v[120:123]
	v_mfma_f32_16x16x32_bf16 v[124:127], v[200:203], v[24:27], v[124:127]
	v_fma_f32 v70, v30, v34, v96
	v_fma_f32 v71, v30, v35, v100
	v_fma_f32 v72, v10, v35, v70
	v_fma_f32 v73, v11, v34, v71
	v_fma_f32 v70, v30, v72, v97
	v_fma_f32 v71, v30, v73, v101
	v_fma_f32 v34, v10, v73, v70
	v_fma_f32 v35, v11, v72, v71
	v_mfma_f32_16x16x32_bf16 v[128:131], v[204:207], v[12:15], 0
	v_mfma_f32_16x16x32_bf16 v[132:135], v[204:207], v[20:23], 0
	v_mfma_f32_16x16x32_bf16 v[128:131], v[212:215], v[16:19], v[128:131]
	v_mfma_f32_16x16x32_bf16 v[132:135], v[212:215], v[24:27], v[132:135]
	ds_read_b128 v[156:159], v196 offset:256
	ds_read_b128 v[200:203], v197 offset:256
	ds_read_b128 v[204:207], v196 offset:384
	ds_read_b128 v[212:215], v197 offset:384
	v_fma_f32 v70, v30, v34, v98
	v_fma_f32 v71, v30, v35, v102
	v_fma_f32 v72, v10, v35, v70
	v_fma_f32 v73, v11, v34, v71
	v_fma_f32 v70, v30, v72, v99
	v_fma_f32 v71, v30, v73, v103
	v_fma_f32 v34, v10, v73, v70
	v_fma_f32 v35, v11, v72, v71
	v_fma_f32 v70, v30, v34, v104
	v_fma_f32 v71, v30, v35, v108
	v_fma_f32 v72, v10, v35, v70
	v_fma_f32 v73, v11, v34, v71
	v_fma_f32 v70, v30, v72, v105
	v_fma_f32 v71, v30, v73, v109
	v_fma_f32 v34, v10, v73, v70
	v_fma_f32 v35, v11, v72, v71
	s_waitcnt lgkmcnt(0)
	v_mfma_f32_16x16x32_bf16 v[136:139], v[156:159], v[12:15], 0
	v_mfma_f32_16x16x32_bf16 v[140:143], v[156:159], v[20:23], 0
	v_mfma_f32_16x16x32_bf16 v[136:139], v[200:203], v[16:19], v[136:139]
	v_mfma_f32_16x16x32_bf16 v[140:143], v[200:203], v[24:27], v[140:143]
	v_fma_f32 v70, v30, v34, v106
	v_fma_f32 v71, v30, v35, v110
	v_fma_f32 v72, v10, v35, v70
	v_fma_f32 v73, v11, v34, v71
	v_fma_f32 v70, v30, v72, v107
	v_fma_f32 v71, v30, v73, v111
	v_fma_f32 v34, v10, v73, v70
	v_fma_f32 v35, v11, v72, v71
	v_mfma_f32_16x16x32_bf16 v[148:151], v[204:207], v[12:15], 0
	v_mfma_f32_16x16x32_bf16 v[152:155], v[204:207], v[20:23], 0
	v_mfma_f32_16x16x32_bf16 v[148:151], v[212:215], v[16:19], v[148:151]
	v_mfma_f32_16x16x32_bf16 v[152:155], v[212:215], v[24:27], v[152:155]
	v_fma_f32 v70, v30, v34, v112
	v_fma_f32 v71, v30, v35, v116
	v_fma_f32 v72, v10, v35, v70
	v_fma_f32 v73, v11, v34, v71
	v_fma_f32 v70, v30, v72, v113
	v_fma_f32 v71, v30, v73, v117
	v_fma_f32 v34, v10, v73, v70
	v_fma_f32 v35, v11, v72, v71
	v_fma_f32 v70, v30, v34, v114
	v_fma_f32 v71, v30, v35, v118
	v_fma_f32 v72, v10, v35, v70
	v_fma_f32 v73, v11, v34, v71
	v_fma_f32 v70, v30, v72, v115
	v_fma_f32 v71, v30, v73, v119
	v_fma_f32 v34, v10, v73, v70
	v_fma_f32 v35, v11, v72, v71
	s_waitcnt vmcnt(9)
	ds_write_b64 v146, v[36:37]
	ds_read_b128 v[156:159], v196 offset:0
	ds_read_b128 v[200:203], v197 offset:0
	ds_read_b128 v[204:207], v196 offset:128
	ds_read_b128 v[212:215], v197 offset:128
	global_load_dwordx2 v[48:49], v[54:55], off
	v_lshl_add_u64 v[54:55], v[54:55], 0, s[20:21]
	v_cvt_pk_bf16_f32 v82, v60, v61
	v_cvt_pk_bf16_f32 v83, v62, v63
	v_cvt_pk_bf16_f32 v84, v64, v65
	v_cvt_pk_bf16_f32 v85, v66, v67
	global_store_dwordx4 v[58:59], v[82:85], off
	s_mov_b64 s[22:23], 0x200000
	v_lshl_add_u64 v[58:59], v[58:59], 0, s[22:23]
	v_fma_f32 v70, v30, v34, v120
	v_fma_f32 v71, v30, v35, v124
	v_fma_f32 v72, v10, v35, v70
	v_fma_f32 v73, v11, v34, v71
	v_fma_f32 v70, v30, v72, v121
	v_fma_f32 v71, v30, v73, v125
	v_fma_f32 v34, v10, v73, v70
	v_fma_f32 v35, v11, v72, v71
	v_fma_f32 v70, v30, v34, v122
	v_fma_f32 v71, v30, v35, v126
	v_fma_f32 v72, v10, v35, v70
	v_fma_f32 v73, v11, v34, v71
	v_fma_f32 v70, v30, v72, v123
	v_fma_f32 v71, v30, v73, v127
	v_fma_f32 v34, v10, v73, v70
	v_fma_f32 v35, v11, v72, v71
	s_waitcnt lgkmcnt(0)
	v_mfma_f32_16x16x32_bf16 v[88:91], v[156:159], v[12:15], 0
	v_mfma_f32_16x16x32_bf16 v[92:95], v[156:159], v[20:23], 0
	v_mfma_f32_16x16x32_bf16 v[88:91], v[200:203], v[16:19], v[88:91]
	v_mfma_f32_16x16x32_bf16 v[92:95], v[200:203], v[24:27], v[92:95]
	v_fma_f32 v70, v30, v34, v128
	v_fma_f32 v71, v30, v35, v132
	v_fma_f32 v72, v10, v35, v70
	v_fma_f32 v73, v11, v34, v71
	v_fma_f32 v70, v30, v72, v129
	v_fma_f32 v71, v30, v73, v133
	v_fma_f32 v34, v10, v73, v70
	v_fma_f32 v35, v11, v72, v71
	v_mfma_f32_16x16x32_bf16 v[96:99], v[204:207], v[12:15], 0
	v_mfma_f32_16x16x32_bf16 v[100:103], v[204:207], v[20:23], 0
	v_mfma_f32_16x16x32_bf16 v[96:99], v[212:215], v[16:19], v[96:99]
	v_mfma_f32_16x16x32_bf16 v[100:103], v[212:215], v[24:27], v[100:103]
	ds_read_b128 v[156:159], v196 offset:256
	ds_read_b128 v[200:203], v197 offset:256
	ds_read_b128 v[204:207], v196 offset:384
	ds_read_b128 v[212:215], v197 offset:384
	v_fma_f32 v70, v30, v34, v130
	v_fma_f32 v71, v30, v35, v134
	v_fma_f32 v72, v10, v35, v70
	v_fma_f32 v73, v11, v34, v71
	v_fma_f32 v70, v30, v72, v131
	v_fma_f32 v71, v30, v73, v135
	v_fma_f32 v34, v10, v73, v70
	v_fma_f32 v35, v11, v72, v71
	v_fma_f32 v70, v30, v34, v136
	v_fma_f32 v71, v30, v35, v140
	v_fma_f32 v72, v10, v35, v70
	v_fma_f32 v73, v11, v34, v71
	v_fma_f32 v70, v30, v72, v137
	v_fma_f32 v71, v30, v73, v141
	v_fma_f32 v34, v10, v73, v70
	v_fma_f32 v35, v11, v72, v71
	s_waitcnt lgkmcnt(0)
	v_mfma_f32_16x16x32_bf16 v[104:107], v[156:159], v[12:15], 0
	v_mfma_f32_16x16x32_bf16 v[108:111], v[156:159], v[20:23], 0
	v_mfma_f32_16x16x32_bf16 v[104:107], v[200:203], v[16:19], v[104:107]
	v_mfma_f32_16x16x32_bf16 v[108:111], v[200:203], v[24:27], v[108:111]
	v_fma_f32 v70, v30, v34, v138
	v_fma_f32 v71, v30, v35, v142
	v_fma_f32 v72, v10, v35, v70
	v_fma_f32 v73, v11, v34, v71
	v_fma_f32 v70, v30, v72, v139
	v_fma_f32 v71, v30, v73, v143
	v_fma_f32 v34, v10, v73, v70
	v_fma_f32 v35, v11, v72, v71
	v_mfma_f32_16x16x32_bf16 v[112:115], v[204:207], v[12:15], 0
	v_mfma_f32_16x16x32_bf16 v[116:119], v[204:207], v[20:23], 0
	v_mfma_f32_16x16x32_bf16 v[112:115], v[212:215], v[16:19], v[112:115]
	v_mfma_f32_16x16x32_bf16 v[116:119], v[212:215], v[24:27], v[116:119]
	v_fma_f32 v70, v30, v34, v148
	v_fma_f32 v71, v30, v35, v152
	v_fma_f32 v72, v10, v35, v70
	v_fma_f32 v73, v11, v34, v71
	v_fma_f32 v70, v30, v72, v149
	v_fma_f32 v71, v30, v73, v153
	v_fma_f32 v34, v10, v73, v70
	v_fma_f32 v35, v11, v72, v71
	v_fma_f32 v70, v30, v34, v150
	v_fma_f32 v71, v30, v35, v154
	v_fma_f32 v72, v10, v35, v70
	v_fma_f32 v73, v11, v34, v71
	v_fma_f32 v70, v30, v72, v151
	v_fma_f32 v71, v30, v73, v155
	v_fma_f32 v34, v10, v73, v70
	v_fma_f32 v35, v11, v72, v71
	s_add_u32 s12, s12, 8
	s_cmp_eq_u32 s12, 64
	s_cbranch_scc0 .Lp1_loop
	s_waitcnt vmcnt(0)
	v_cvt_pk_bf16_f32 v82, v74, v75
	v_cvt_pk_bf16_f32 v83, v76, v77
	v_cvt_pk_bf16_f32 v84, v78, v79
	v_cvt_pk_bf16_f32 v85, v80, v81
	global_store_dwordx4 v[58:59], v[82:85], off
	s_mov_b64 s[22:23], 0x200000
	v_lshl_add_u64 v[58:59], v[58:59], 0, s[22:23]
	s_waitcnt lgkmcnt(0)
	s_branch .LBB0_338
; __device__ __forceinline__ float bf2f(bf16_t v) { return __uint_as_float(((unsigned)v) << 16); }
; template <int W> __device__ __forceinline__ void pool_round2(const bf16_t* zpa, bf16_t* mpa, const bf16_t* zpb, bf16_t* mpb, int t0) {
;     float a[W - 1 + 16], c[W - 1 + 16];
; #pragma unroll
;     for (int i = 0; i < W - 1 + 16; ++i) { const int t = t0 - (W - 1) + i; a[i] = (t >= 0) ? bf2f(zpa[(size_t)t * DM]) : 0.f; c[i] = (t >= 0) ? bf2f(zpb[(size_t)t * DM]) : 0.f; }
;     float sa = 0.f, sc = 0.f;
; #pragma unroll
;     for (int i = 0; i < W - 1; ++i) { sa += a[i]; sc += c[i]; }
; __device__ void pool_phase(const Params& P) {
;     int tid = threadIdx.x; asm volatile("" : "+v"(tid));
;     const int G = gridDim.x; unsigned char* ws = P.ws;
;     const bf16_t* z = (const bf16_t*)(ws + WS_BIG + BIG_Z); bf16_t* mix = (bf16_t*)(ws + WS_BIG + BIG_MIX);
;     const int ch = tid, gi = __builtin_amdgcn_readfirstlane(ch >> 7);
;     for (int q = blockIdx.x; q < 2048; q += G) {
;         const int t0 = (q & 255) * 16, b0 = (q >> 8) * 2;
;         const bf16_t* zpa = z + (size_t)b0 * SEQ * DM + 512 + ch; bf16_t* mpa = mix + (size_t)b0 * SEQ * DM + 512 + ch;
;         const bf16_t* zpb = zpa + (size_t)SEQ * DM; bf16_t* mpb = mpa + (size_t)SEQ * DM;
;         if (gi == 0) pool_round2<2>(zpa, mpa, zpb, mpb, t0); else if (gi == 1) pool_round2<4>(zpa, mpa, zpb, mpb, t0); else if (gi == 2) pool_round2<8>(zpa, mpa, zpb, mpb, t0); else pool_round2<16>(zpa, mpa, zpb, mpb, t0);
.LBB0_343:
	v_readfirstlane_b32 s0, v162
	v_readlane_b32 s12, v253, 0
	v_readlane_b32 s18, v253, 8
	v_readlane_b32 s19, v253, 9
	s_lshr_b32 s1, s0, 6
	s_and_b32 s10, s1, 3
	s_lshr_b32 s11, s1, 2
	s_lshl_b32 s13, s12, 4
	s_cmp_lg_u32 s12, 0
	s_cselect_b32 s14, -1, 0
	s_add_u32 s18, s18, 0x10000000
	s_addc_u32 s19, s19, 0
	s_lshl_b32 s22, s11, 12
	s_add_u32 s22, s22, s13
	s_lshl_b32 s22, s22, 11
	s_add_u32 s18, s18, s22
	s_addc_u32 s19, s19, 0
	s_lshl_b32 s23, s10, 8
	s_add_u32 s23, s23, 0x400
	v_lshlrev_b32_e32 v0, 2, v208
	v_add_u32_e32 v0, s23, v0
	s_mov_b32 s57, 8
	s_cmp_eq_u32 s10, 0
	s_cbranch_scc1 .Lpool_w2
	s_cmp_eq_u32 s10, 1
	s_cbranch_scc1 .Lpool_w4
	s_cmp_eq_u32 s10, 2
	s_cbranch_scc1 .Lpool_w8
.Lpool_w16:
	s_mov_b32 s56, 0x3d800000
.Lpool_w16_loop:
	s_sub_u32 s26, s18, 0x7800
	s_subb_u32 s27, s19, 0
	global_load_dword v12, v0, s[26:27]
	s_add_u32 s26, s26, 0x800
	s_addc_u32 s27, s27, 0
	global_load_dword v13, v0, s[26:27]
	s_add_u32 s26, s26, 0x800
	s_addc_u32 s27, s27, 0
	global_load_dword v14, v0, s[26:27]
	s_add_u32 s26, s26, 0x800
	s_addc_u32 s27, s27, 0
	global_load_dword v15, v0, s[26:27]
	s_add_u32 s26, s26, 0x800
	s_addc_u32 s27, s27, 0
	global_load_dword v16, v0, s[26:27]
	s_add_u32 s26, s26, 0x800
	s_addc_u32 s27, s27, 0
	global_load_dword v17, v0, s[26:27]
	s_add_u32 s26, s26, 0x800
	s_addc_u32 s27, s27, 0
	global_load_dword v18, v0, s[26:27]
	s_add_u32 s26, s26, 0x800
	s_addc_u32 s27, s27, 0
	global_load_dword v19, v0, s[26:27]
	s_add_u32 s26, s26, 0x800
	s_addc_u32 s27, s27, 0
	global_load_dword v20, v0, s[26:27]
	s_add_u32 s26, s26, 0x800
	s_addc_u32 s27, s27, 0
	global_load_dword v21, v0, s[26:27]
	s_add_u32 s26, s26, 0x800
	s_addc_u32 s27, s27, 0
	global_load_dword v22, v0, s[26:27]
	s_add_u32 s26, s26, 0x800
	s_addc_u32 s27, s27, 0
	global_load_dword v23, v0, s[26:27]
	s_add_u32 s26, s26, 0x800
	s_addc_u32 s27, s27, 0
	global_load_dword v24, v0, s[26:27]
	s_add_u32 s26, s26, 0x800
	s_addc_u32 s27, s27, 0
	global_load_dword v25, v0, s[26:27]
	s_add_u32 s26, s26, 0x800
	s_addc_u32 s27, s27, 0
	global_load_dword v26, v0, s[26:27]
	s_add_u32 s26, s26, 0x800
	s_addc_u32 s27, s27, 0
	global_load_dword v27, v0, s[26:27]
	s_add_u32 s26, s26, 0x800
	s_addc_u32 s27, s27, 0
	global_load_dword v28, v0, s[26:27]
	s_add_u32 s26, s26, 0x800
	s_addc_u32 s27, s27, 0
	global_load_dword v29, v0, s[26:27]
	s_add_u32 s26, s26, 0x800
	s_addc_u32 s27, s27, 0
	global_load_dword v30, v0, s[26:27]
	s_add_u32 s26, s26, 0x800
	s_addc_u32 s27, s27, 0
	global_load_dword v31, v0, s[26:27]
	s_add_u32 s26, s26, 0x800
	s_addc_u32 s27, s27, 0
	global_load_dword v32, v0, s[26:27]
	s_add_u32 s26, s26, 0x800
	s_addc_u32 s27, s27, 0
	global_load_dword v33, v0, s[26:27]
	s_add_u32 s26, s26, 0x800
	s_addc_u32 s27, s27, 0
	global_load_dword v34, v0, s[26:27]
	s_add_u32 s26, s26, 0x800
	s_addc_u32 s27, s27, 0
	global_load_dword v35, v0, s[26:27]
	s_add_u32 s26, s26, 0x800
	s_addc_u32 s27, s27, 0
	global_load_dword v36, v0, s[26:27]
	s_add_u32 s26, s26, 0x800
	s_addc_u32 s27, s27, 0
	global_load_dword v37, v0, s[26:27]
	s_add_u32 s26, s26, 0x800
	s_addc_u32 s27, s27, 0
	global_load_dword v38, v0, s[26:27]
	s_add_u32 s26, s26, 0x800
	s_addc_u32 s27, s27, 0
	global_load_dword v39, v0, s[26:27]
	s_add_u32 s26, s26, 0x800
	s_addc_u32 s27, s27, 0
	global_load_dword v40, v0, s[26:27]
	s_add_u32 s26, s26, 0x800
	s_addc_u32 s27, s27, 0
	global_load_dword v41, v0, s[26:27]
	s_add_u32 s26, s26, 0x800
	s_addc_u32 s27, s27, 0
	global_load_dword v42, v0, s[26:27]
	s_add_u32 s28, s18, 0x8000000
	s_addc_u32 s29, s19, 0
	s_waitcnt vmcnt(0)
	v_and_b32_e32 v12, s14, v12
	v_and_b32_e32 v13, s14, v13
	v_and_b32_e32 v14, s14, v14
	v_and_b32_e32 v15, s14, v15
	v_and_b32_e32 v16, s14, v16
	v_and_b32_e32 v17, s14, v17
	v_and_b32_e32 v18, s14, v18
	v_and_b32_e32 v19, s14, v19
	v_and_b32_e32 v20, s14, v20
	v_and_b32_e32 v21, s14, v21
	v_and_b32_e32 v22, s14, v22
	v_and_b32_e32 v23, s14, v23
	v_and_b32_e32 v24, s14, v24
	v_and_b32_e32 v25, s14, v25
	v_and_b32_e32 v26, s14, v26
	v_and_b32_e32 v82, 0xffff0000, v12
	v_lshlrev_b32_e32 v12, 16, v12
	v_and_b32_e32 v83, 0xffff0000, v13
	v_lshlrev_b32_e32 v13, 16, v13
	v_and_b32_e32 v84, 0xffff0000, v14
	v_lshlrev_b32_e32 v14, 16, v14
	v_and_b32_e32 v85, 0xffff0000, v15
	v_lshlrev_b32_e32 v15, 16, v15
	v_and_b32_e32 v86, 0xffff0000, v16
	v_lshlrev_b32_e32 v16, 16, v16
	v_and_b32_e32 v87, 0xffff0000, v17
	v_lshlrev_b32_e32 v17, 16, v17
	v_and_b32_e32 v88, 0xffff0000, v18
	v_lshlrev_b32_e32 v18, 16, v18
	v_and_b32_e32 v89, 0xffff0000, v19
	v_lshlrev_b32_e32 v19, 16, v19
	v_and_b32_e32 v90, 0xffff0000, v20
	v_lshlrev_b32_e32 v20, 16, v20
	v_and_b32_e32 v91, 0xffff0000, v21
	v_lshlrev_b32_e32 v21, 16, v21
	v_and_b32_e32 v92, 0xffff0000, v22
	v_lshlrev_b32_e32 v22, 16, v22
	v_and_b32_e32 v93, 0xffff0000, v23
	v_lshlrev_b32_e32 v23, 16, v23
	v_and_b32_e32 v94, 0xffff0000, v24
	v_lshlrev_b32_e32 v24, 16, v24
	v_and_b32_e32 v95, 0xffff0000, v25
	v_lshlrev_b32_e32 v25, 16, v25
	v_and_b32_e32 v96, 0xffff0000, v26
	v_lshlrev_b32_e32 v26, 16, v26
	v_and_b32_e32 v97, 0xffff0000, v27
	v_lshlrev_b32_e32 v27, 16, v27
	v_and_b32_e32 v98, 0xffff0000, v28
	v_lshlrev_b32_e32 v28, 16, v28
	v_and_b32_e32 v99, 0xffff0000, v29
	v_lshlrev_b32_e32 v29, 16, v29
	v_and_b32_e32 v100, 0xffff0000, v30
	v_lshlrev_b32_e32 v30, 16, v30
	v_and_b32_e32 v101, 0xffff0000, v31
	v_lshlrev_b32_e32 v31, 16, v31
	v_and_b32_e32 v102, 0xffff0000, v32
	v_lshlrev_b32_e32 v32, 16, v32
	v_and_b32_e32 v103, 0xffff0000, v33
	v_lshlrev_b32_e32 v33, 16, v33
	v_and_b32_e32 v104, 0xffff0000, v34
	v_lshlrev_b32_e32 v34, 16, v34
	v_and_b32_e32 v105, 0xffff0000, v35
	v_lshlrev_b32_e32 v35, 16, v35
; __device__ __forceinline__ bf16_t f2bf(float f) { unsigned u = __float_as_uint(f); u += 0x7FFFu + ((u >> 16) & 1u); return (bf16_t)(u >> 16); }
; __device__ __forceinline__ float bf2f(bf16_t v) { return __uint_as_float(((unsigned)v) << 16); }
; template <int W> __device__ __forceinline__ void pool_round2(const bf16_t* zpa, bf16_t* mpa, const bf16_t* zpb, bf16_t* mpb, int t0) {
;     float a[W - 1 + 16], c[W - 1 + 16];
; #pragma unroll
;     for (int i = 0; i < W - 1 + 16; ++i) { const int t = t0 - (W - 1) + i; a[i] = (t >= 0) ? bf2f(zpa[(size_t)t * DM]) : 0.f; c[i] = (t >= 0) ? bf2f(zpb[(size_t)t * DM]) : 0.f; }
;     float sa = 0.f, sc = 0.f;
; #pragma unroll
;     for (int i = 0; i < W - 1; ++i) { sa += a[i]; sc += c[i]; }
; #pragma unroll
;     for (int j = 0; j < 16; ++j) {
;         const int t = t0 + j; const float va = a[W - 1 + j], vc = c[W - 1 + j]; sa += va; sc += vc;
;         const float inv = 1.0f / (float)((t + 1 < W) ? t + 1 : W);
;         mpa[(size_t)t * DM] = f2bf(sa * inv - va); mpb[(size_t)t * DM] = f2bf(sc * inv - vc);
;         sa -= a[j]; sc -= c[j];
;     }
; }
	v_and_b32_e32 v106, 0xffff0000, v36
	v_lshlrev_b32_e32 v36, 16, v36
	v_and_b32_e32 v107, 0xffff0000, v37
	v_lshlrev_b32_e32 v37, 16, v37
	v_and_b32_e32 v108, 0xffff0000, v38
	v_lshlrev_b32_e32 v38, 16, v38
	v_and_b32_e32 v109, 0xffff0000, v39
	v_lshlrev_b32_e32 v39, 16, v39
	v_and_b32_e32 v110, 0xffff0000, v40
	v_lshlrev_b32_e32 v40, 16, v40
	v_and_b32_e32 v111, 0xffff0000, v41
	v_lshlrev_b32_e32 v41, 16, v41
	v_and_b32_e32 v112, 0xffff0000, v42
	v_lshlrev_b32_e32 v42, 16, v42
	v_add_f32_e32 v4, 0, v12
	v_add_f32_e32 v5, 0, v82
	v_add_f32_e32 v4, v4, v13
	v_add_f32_e32 v5, v5, v83
	v_add_f32_e32 v4, v4, v14
	v_add_f32_e32 v5, v5, v84
	v_add_f32_e32 v4, v4, v15
	v_add_f32_e32 v5, v5, v85
	v_add_f32_e32 v4, v4, v16
	v_add_f32_e32 v5, v5, v86
	v_add_f32_e32 v4, v4, v17
	v_add_f32_e32 v5, v5, v87
	v_add_f32_e32 v4, v4, v18
	v_add_f32_e32 v5, v5, v88
	v_add_f32_e32 v4, v4, v19
	v_add_f32_e32 v5, v5, v89
	v_add_f32_e32 v4, v4, v20
	v_add_f32_e32 v5, v5, v90
	v_add_f32_e32 v4, v4, v21
	v_add_f32_e32 v5, v5, v91
	v_add_f32_e32 v4, v4, v22
	v_add_f32_e32 v5, v5, v92
	v_add_f32_e32 v4, v4, v23
	v_add_f32_e32 v5, v5, v93
	v_add_f32_e32 v4, v4, v24
	v_add_f32_e32 v5, v5, v94
	v_add_f32_e32 v4, v4, v25
	v_add_f32_e32 v5, v5, v95
	v_add_f32_e32 v4, v4, v26
	v_add_f32_e32 v5, v5, v96
	s_cmp_eq_u32 s12, 0
	s_cselect_b32 s32, 0x3f800000, s56
	v_add_f32_e32 v4, v4, v27
	v_add_f32_e32 v5, v5, v97
	v_fma_f32 v6, s32, v4, -v27
	v_fma_f32 v7, s32, v5, -v97
	v_sub_f32_e32 v4, v4, v12
	v_sub_f32_e32 v5, v5, v82
	v_cvt_pk_bf16_f32 v113, v6, v7
	global_store_dword v0, v113, s[28:29]
	s_add_u32 s28, s28, 0x800
	s_addc_u32 s29, s29, 0
	s_cmp_eq_u32 s12, 0
	s_cselect_b32 s32, 0x3f000000, s56
	v_add_f32_e32 v4, v4, v28
	v_add_f32_e32 v5, v5, v98
	v_fma_f32 v6, s32, v4, -v28
	v_fma_f32 v7, s32, v5, -v98
	v_sub_f32_e32 v4, v4, v13
	v_sub_f32_e32 v5, v5, v83
	v_cvt_pk_bf16_f32 v114, v6, v7
	global_store_dword v0, v114, s[28:29]
	s_add_u32 s28, s28, 0x800
	s_addc_u32 s29, s29, 0
	s_cmp_eq_u32 s12, 0
	s_cselect_b32 s32, 0x3eaaaaab, s56
	v_add_f32_e32 v4, v4, v29
	v_add_f32_e32 v5, v5, v99
	v_fma_f32 v6, s32, v4, -v29
	v_fma_f32 v7, s32, v5, -v99
	v_sub_f32_e32 v4, v4, v14
	v_sub_f32_e32 v5, v5, v84
	v_cvt_pk_bf16_f32 v115, v6, v7
	global_store_dword v0, v115, s[28:29]
	s_add_u32 s28, s28, 0x800
	s_addc_u32 s29, s29, 0
	s_cmp_eq_u32 s12, 0
	s_cselect_b32 s32, 0x3e800000, s56
	v_add_f32_e32 v4, v4, v30
	v_add_f32_e32 v5, v5, v100
	v_fma_f32 v6, s32, v4, -v30
	v_fma_f32 v7, s32, v5, -v100
	v_sub_f32_e32 v4, v4, v15
	v_sub_f32_e32 v5, v5, v85
	v_cvt_pk_bf16_f32 v116, v6, v7
	global_store_dword v0, v116, s[28:29]
	s_add_u32 s28, s28, 0x800
	s_addc_u32 s29, s29, 0
	s_cmp_eq_u32 s12, 0
	s_cselect_b32 s32, 0x3e4ccccd, s56
	v_add_f32_e32 v4, v4, v31
	v_add_f32_e32 v5, v5, v101
	v_fma_f32 v6, s32, v4, -v31
	v_fma_f32 v7, s32, v5, -v101
	v_sub_f32_e32 v4, v4, v16
	v_sub_f32_e32 v5, v5, v86
	v_cvt_pk_bf16_f32 v117, v6, v7
	global_store_dword v0, v117, s[28:29]
	s_add_u32 s28, s28, 0x800
	s_addc_u32 s29, s29, 0
	s_cmp_eq_u32 s12, 0
	s_cselect_b32 s32, 0x3e2aaaab, s56
	v_add_f32_e32 v4, v4, v32
	v_add_f32_e32 v5, v5, v102
	v_fma_f32 v6, s32, v4, -v32
	v_fma_f32 v7, s32, v5, -v102
	v_sub_f32_e32 v4, v4, v17
	v_sub_f32_e32 v5, v5, v87
	v_cvt_pk_bf16_f32 v118, v6, v7
	global_store_dword v0, v118, s[28:29]
	s_add_u32 s28, s28, 0x800
	s_addc_u32 s29, s29, 0
	s_cmp_eq_u32 s12, 0
	s_cselect_b32 s32, 0x3e124925, s56
	v_add_f32_e32 v4, v4, v33
	v_add_f32_e32 v5, v5, v103
	v_fma_f32 v6, s32, v4, -v33
	v_fma_f32 v7, s32, v5, -v103
	v_sub_f32_e32 v4, v4, v18
	v_sub_f32_e32 v5, v5, v88
	v_cvt_pk_bf16_f32 v119, v6, v7
	global_store_dword v0, v119, s[28:29]
	s_add_u32 s28, s28, 0x800
	s_addc_u32 s29, s29, 0
	s_cmp_eq_u32 s12, 0
	s_cselect_b32 s32, 0x3e000000, s56
	v_add_f32_e32 v4, v4, v34
	v_add_f32_e32 v5, v5, v104
	v_fma_f32 v6, s32, v4, -v34
	v_fma_f32 v7, s32, v5, -v104
	v_sub_f32_e32 v4, v4, v19
	v_sub_f32_e32 v5, v5, v89
	v_cvt_pk_bf16_f32 v120, v6, v7
	global_store_dword v0, v120, s[28:29]
	s_add_u32 s28, s28, 0x800
	s_addc_u32 s29, s29, 0
	s_cmp_eq_u32 s12, 0
	s_cselect_b32 s32, 0x3de38e39, s56
	v_add_f32_e32 v4, v4, v35
	v_add_f32_e32 v5, v5, v105
	v_fma_f32 v6, s32, v4, -v35
	v_fma_f32 v7, s32, v5, -v105
	v_sub_f32_e32 v4, v4, v20
	v_sub_f32_e32 v5, v5, v90
	v_cvt_pk_bf16_f32 v121, v6, v7
	global_store_dword v0, v121, s[28:29]
	s_add_u32 s28, s28, 0x800
	s_addc_u32 s29, s29, 0
	s_cmp_eq_u32 s12, 0
	s_cselect_b32 s32, 0x3dcccccd, s56
	v_add_f32_e32 v4, v4, v36
	v_add_f32_e32 v5, v5, v106
	v_fma_f32 v6, s32, v4, -v36
	v_fma_f32 v7, s32, v5, -v106
	v_sub_f32_e32 v4, v4, v21
	v_sub_f32_e32 v5, v5, v91
	v_cvt_pk_bf16_f32 v122, v6, v7
	global_store_dword v0, v122, s[28:29]
	s_add_u32 s28, s28, 0x800
	s_addc_u32 s29, s29, 0
	s_cmp_eq_u32 s12, 0
	s_cselect_b32 s32, 0x3dba2e8c, s56
	v_add_f32_e32 v4, v4, v37
	v_add_f32_e32 v5, v5, v107
	v_fma_f32 v6, s32, v4, -v37
	v_fma_f32 v7, s32, v5, -v107
	v_sub_f32_e32 v4, v4, v22
	v_sub_f32_e32 v5, v5, v92
	v_cvt_pk_bf16_f32 v123, v6, v7
	global_store_dword v0, v123, s[28:29]
	s_add_u32 s28, s28, 0x800
	s_addc_u32 s29, s29, 0
	s_cmp_eq_u32 s12, 0
	s_cselect_b32 s32, 0x3daaaaab, s56
	v_add_f32_e32 v4, v4, v38
	v_add_f32_e32 v5, v5, v108
	v_fma_f32 v6, s32, v4, -v38
	v_fma_f32 v7, s32, v5, -v108
	v_sub_f32_e32 v4, v4, v23
	v_sub_f32_e32 v5, v5, v93
	v_cvt_pk_bf16_f32 v124, v6, v7
	global_store_dword v0, v124, s[28:29]
	s_add_u32 s28, s28, 0x800
	s_addc_u32 s29, s29, 0
	s_cmp_eq_u32 s12, 0
	s_cselect_b32 s32, 0x3d9d89d9, s56
	v_add_f32_e32 v4, v4, v39
	v_add_f32_e32 v5, v5, v109
	v_fma_f32 v6, s32, v4, -v39
	v_fma_f32 v7, s32, v5, -v109
	v_sub_f32_e32 v4, v4, v24
	v_sub_f32_e32 v5, v5, v94
	v_cvt_pk_bf16_f32 v125, v6, v7
	global_store_dword v0, v125, s[28:29]
	s_add_u32 s28, s28, 0x800
	s_addc_u32 s29, s29, 0
	s_cmp_eq_u32 s12, 0
	s_cselect_b32 s32, 0x3d924925, s56
	v_add_f32_e32 v4, v4, v40
	v_add_f32_e32 v5, v5, v110
	v_fma_f32 v6, s32, v4, -v40
	v_fma_f32 v7, s32, v5, -v110
	v_sub_f32_e32 v4, v4, v25
	v_sub_f32_e32 v5, v5, v95
	v_cvt_pk_bf16_f32 v126, v6, v7
	global_store_dword v0, v126, s[28:29]
	s_add_u32 s28, s28, 0x800
	s_addc_u32 s29, s29, 0
	s_cmp_eq_u32 s12, 0
	s_cselect_b32 s32, 0x3d888889, s56
	v_add_f32_e32 v4, v4, v41
	v_add_f32_e32 v5, v5, v111
	v_fma_f32 v6, s32, v4, -v41
	v_fma_f32 v7, s32, v5, -v111
	v_sub_f32_e32 v4, v4, v26
	v_sub_f32_e32 v5, v5, v96
	v_cvt_pk_bf16_f32 v127, v6, v7
	global_store_dword v0, v127, s[28:29]
	s_add_u32 s28, s28, 0x800
	s_addc_u32 s29, s29, 0
	v_add_f32_e32 v4, v4, v42
	v_add_f32_e32 v5, v5, v112
	v_fma_f32 v6, s56, v4, -v42
	v_fma_f32 v7, s56, v5, -v112
	v_sub_f32_e32 v4, v4, v27
	v_sub_f32_e32 v5, v5, v97
	v_cvt_pk_bf16_f32 v128, v6, v7
	global_store_dword v0, v128, s[28:29]
	s_add_u32 s18, s18, 0x1000000
	s_addc_u32 s19, s19, 0
	s_sub_u32 s57, s57, 1
	s_cmp_lg_u32 s57, 0
	s_cbranch_scc1 .Lpool_w16_loop
	s_branch .LBB0_464
; __device__ __forceinline__ bf16_t f2bf(float f) { unsigned u = __float_as_uint(f); u += 0x7FFFu + ((u >> 16) & 1u); return (bf16_t)(u >> 16); }
; __device__ __forceinline__ float bf2f(bf16_t v) { return __uint_as_float(((unsigned)v) << 16); }
; template <int W> __device__ __forceinline__ void pool_round2(const bf16_t* zpa, bf16_t* mpa, const bf16_t* zpb, bf16_t* mpb, int t0) {
;     float a[W - 1 + 16], c[W - 1 + 16];
; #pragma unroll
;     for (int i = 0; i < W - 1 + 16; ++i) { const int t = t0 - (W - 1) + i; a[i] = (t >= 0) ? bf2f(zpa[(size_t)t * DM]) : 0.f; c[i] = (t >= 0) ? bf2f(zpb[(size_t)t * DM]) : 0.f; }
;     float sa = 0.f, sc = 0.f;
; #pragma unroll
;     for (int i = 0; i < W - 1; ++i) { sa += a[i]; sc += c[i]; }
; #pragma unroll
;     for (int j = 0; j < 16; ++j) {
;         const int t = t0 + j; const float va = a[W - 1 + j], vc = c[W - 1 + j]; sa += va; sc += vc;
;         const float inv = 1.0f / (float)((t + 1 < W) ? t + 1 : W);
;         mpa[(size_t)t * DM] = f2bf(sa * inv - va); mpb[(size_t)t * DM] = f2bf(sc * inv - vc);
;         sa -= a[j]; sc -= c[j];
;     }
; }
.Lpool_w8:
	s_mov_b32 s56, 0x3e000000
.Lpool_w8_loop:
	s_sub_u32 s26, s18, 0x3800
	s_subb_u32 s27, s19, 0
	global_load_dword v12, v0, s[26:27]
	s_add_u32 s26, s26, 0x800
	s_addc_u32 s27, s27, 0
	global_load_dword v13, v0, s[26:27]
	s_add_u32 s26, s26, 0x800
	s_addc_u32 s27, s27, 0
	global_load_dword v14, v0, s[26:27]
	s_add_u32 s26, s26, 0x800
	s_addc_u32 s27, s27, 0
	global_load_dword v15, v0, s[26:27]
	s_add_u32 s26, s26, 0x800
	s_addc_u32 s27, s27, 0
	global_load_dword v16, v0, s[26:27]
	s_add_u32 s26, s26, 0x800
	s_addc_u32 s27, s27, 0
	global_load_dword v17, v0, s[26:27]
	s_add_u32 s26, s26, 0x800
	s_addc_u32 s27, s27, 0
	global_load_dword v18, v0, s[26:27]
	s_add_u32 s26, s26, 0x800
	s_addc_u32 s27, s27, 0
	global_load_dword v19, v0, s[26:27]
	s_add_u32 s26, s26, 0x800
	s_addc_u32 s27, s27, 0
	global_load_dword v20, v0, s[26:27]
	s_add_u32 s26, s26, 0x800
	s_addc_u32 s27, s27, 0
	global_load_dword v21, v0, s[26:27]
	s_add_u32 s26, s26, 0x800
	s_addc_u32 s27, s27, 0
	global_load_dword v22, v0, s[26:27]
	s_add_u32 s26, s26, 0x800
	s_addc_u32 s27, s27, 0
	global_load_dword v23, v0, s[26:27]
	s_add_u32 s26, s26, 0x800
	s_addc_u32 s27, s27, 0
	global_load_dword v24, v0, s[26:27]
	s_add_u32 s26, s26, 0x800
	s_addc_u32 s27, s27, 0
	global_load_dword v25, v0, s[26:27]
	s_add_u32 s26, s26, 0x800
	s_addc_u32 s27, s27, 0
	global_load_dword v26, v0, s[26:27]
	s_add_u32 s26, s26, 0x800
	s_addc_u32 s27, s27, 0
	global_load_dword v27, v0, s[26:27]
	s_add_u32 s26, s26, 0x800
	s_addc_u32 s27, s27, 0
	global_load_dword v28, v0, s[26:27]
	s_add_u32 s26, s26, 0x800
	s_addc_u32 s27, s27, 0
	global_load_dword v29, v0, s[26:27]
	s_add_u32 s26, s26, 0x800
	s_addc_u32 s27, s27, 0
	global_load_dword v30, v0, s[26:27]
	s_add_u32 s26, s26, 0x800
	s_addc_u32 s27, s27, 0
	global_load_dword v31, v0, s[26:27]
	s_add_u32 s26, s26, 0x800
	s_addc_u32 s27, s27, 0
	global_load_dword v32, v0, s[26:27]
	s_add_u32 s26, s26, 0x800
	s_addc_u32 s27, s27, 0
	global_load_dword v33, v0, s[26:27]
	s_add_u32 s26, s26, 0x800
	s_addc_u32 s27, s27, 0
	global_load_dword v34, v0, s[26:27]
	s_add_u32 s28, s18, 0x8000000
	s_addc_u32 s29, s19, 0
	s_waitcnt vmcnt(0)
	v_and_b32_e32 v12, s14, v12
	v_and_b32_e32 v13, s14, v13
	v_and_b32_e32 v14, s14, v14
	v_and_b32_e32 v15, s14, v15
	v_and_b32_e32 v16, s14, v16
	v_and_b32_e32 v17, s14, v17
	v_and_b32_e32 v18, s14, v18
	v_and_b32_e32 v82, 0xffff0000, v12
	v_lshlrev_b32_e32 v12, 16, v12
	v_and_b32_e32 v83, 0xffff0000, v13
	v_lshlrev_b32_e32 v13, 16, v13
	v_and_b32_e32 v84, 0xffff0000, v14
	v_lshlrev_b32_e32 v14, 16, v14
	v_and_b32_e32 v85, 0xffff0000, v15
	v_lshlrev_b32_e32 v15, 16, v15
	v_and_b32_e32 v86, 0xffff0000, v16
	v_lshlrev_b32_e32 v16, 16, v16
	v_and_b32_e32 v87, 0xffff0000, v17
	v_lshlrev_b32_e32 v17, 16, v17
	v_and_b32_e32 v88, 0xffff0000, v18
	v_lshlrev_b32_e32 v18, 16, v18
	v_and_b32_e32 v89, 0xffff0000, v19
	v_lshlrev_b32_e32 v19, 16, v19
	v_and_b32_e32 v90, 0xffff0000, v20
	v_lshlrev_b32_e32 v20, 16, v20
	v_and_b32_e32 v91, 0xffff0000, v21
	v_lshlrev_b32_e32 v21, 16, v21
	v_and_b32_e32 v92, 0xffff0000, v22
	v_lshlrev_b32_e32 v22, 16, v22
	v_and_b32_e32 v93, 0xffff0000, v23
	v_lshlrev_b32_e32 v23, 16, v23
	v_and_b32_e32 v94, 0xffff0000, v24
	v_lshlrev_b32_e32 v24, 16, v24
	v_and_b32_e32 v95, 0xffff0000, v25
	v_lshlrev_b32_e32 v25, 16, v25
	v_and_b32_e32 v96, 0xffff0000, v26
	v_lshlrev_b32_e32 v26, 16, v26
	v_and_b32_e32 v97, 0xffff0000, v27
	v_lshlrev_b32_e32 v27, 16, v27
	v_and_b32_e32 v98, 0xffff0000, v28
	v_lshlrev_b32_e32 v28, 16, v28
	v_and_b32_e32 v99, 0xffff0000, v29
	v_lshlrev_b32_e32 v29, 16, v29
	v_and_b32_e32 v100, 0xffff0000, v30
	v_lshlrev_b32_e32 v30, 16, v30
	v_and_b32_e32 v101, 0xffff0000, v31
	v_lshlrev_b32_e32 v31, 16, v31
	v_and_b32_e32 v102, 0xffff0000, v32
	v_lshlrev_b32_e32 v32, 16, v32
	v_and_b32_e32 v103, 0xffff0000, v33
	v_lshlrev_b32_e32 v33, 16, v33
	v_and_b32_e32 v104, 0xffff0000, v34
	v_lshlrev_b32_e32 v34, 16, v34
	v_add_f32_e32 v4, 0, v12
	v_add_f32_e32 v5, 0, v82
	v_add_f32_e32 v4, v4, v13
	v_add_f32_e32 v5, v5, v83
	v_add_f32_e32 v4, v4, v14
	v_add_f32_e32 v5, v5, v84
	v_add_f32_e32 v4, v4, v15
	v_add_f32_e32 v5, v5, v85
	v_add_f32_e32 v4, v4, v16
	v_add_f32_e32 v5, v5, v86
	v_add_f32_e32 v4, v4, v17
	v_add_f32_e32 v5, v5, v87
	v_add_f32_e32 v4, v4, v18
	v_add_f32_e32 v5, v5, v88
	s_cmp_eq_u32 s12, 0
	s_cselect_b32 s32, 0x3f800000, s56
	v_add_f32_e32 v4, v4, v19
	v_add_f32_e32 v5, v5, v89
	v_fma_f32 v6, s32, v4, -v19
	v_fma_f32 v7, s32, v5, -v89
	v_sub_f32_e32 v4, v4, v12
	v_sub_f32_e32 v5, v5, v82
	v_cvt_pk_bf16_f32 v113, v6, v7
	global_store_dword v0, v113, s[28:29]
	s_add_u32 s28, s28, 0x800
	s_addc_u32 s29, s29, 0
	s_cmp_eq_u32 s12, 0
	s_cselect_b32 s32, 0x3f000000, s56
	v_add_f32_e32 v4, v4, v20
	v_add_f32_e32 v5, v5, v90
	v_fma_f32 v6, s32, v4, -v20
	v_fma_f32 v7, s32, v5, -v90
	v_sub_f32_e32 v4, v4, v13
	v_sub_f32_e32 v5, v5, v83
	v_cvt_pk_bf16_f32 v114, v6, v7
	global_store_dword v0, v114, s[28:29]
	s_add_u32 s28, s28, 0x800
	s_addc_u32 s29, s29, 0
	s_cmp_eq_u32 s12, 0
	s_cselect_b32 s32, 0x3eaaaaab, s56
	v_add_f32_e32 v4, v4, v21
	v_add_f32_e32 v5, v5, v91
	v_fma_f32 v6, s32, v4, -v21
	v_fma_f32 v7, s32, v5, -v91
	v_sub_f32_e32 v4, v4, v14
	v_sub_f32_e32 v5, v5, v84
	v_cvt_pk_bf16_f32 v115, v6, v7
	global_store_dword v0, v115, s[28:29]
	s_add_u32 s28, s28, 0x800
	s_addc_u32 s29, s29, 0
	s_cmp_eq_u32 s12, 0
	s_cselect_b32 s32, 0x3e800000, s56
	v_add_f32_e32 v4, v4, v22
	v_add_f32_e32 v5, v5, v92
	v_fma_f32 v6, s32, v4, -v22
	v_fma_f32 v7, s32, v5, -v92
	v_sub_f32_e32 v4, v4, v15
	v_sub_f32_e32 v5, v5, v85
	v_cvt_pk_bf16_f32 v116, v6, v7
	global_store_dword v0, v116, s[28:29]
; __device__ __forceinline__ bf16_t f2bf(float f) { unsigned u = __float_as_uint(f); u += 0x7FFFu + ((u >> 16) & 1u); return (bf16_t)(u >> 16); }
; __device__ __forceinline__ float bf2f(bf16_t v) { return __uint_as_float(((unsigned)v) << 16); }
; template <int W> __device__ __forceinline__ void pool_round2(const bf16_t* zpa, bf16_t* mpa, const bf16_t* zpb, bf16_t* mpb, int t0) {
;     float a[W - 1 + 16], c[W - 1 + 16];
; #pragma unroll
;     for (int i = 0; i < W - 1 + 16; ++i) { const int t = t0 - (W - 1) + i; a[i] = (t >= 0) ? bf2f(zpa[(size_t)t * DM]) : 0.f; c[i] = (t >= 0) ? bf2f(zpb[(size_t)t * DM]) : 0.f; }
;     float sa = 0.f, sc = 0.f;
; #pragma unroll
;     for (int i = 0; i < W - 1; ++i) { sa += a[i]; sc += c[i]; }
; #pragma unroll
;     for (int j = 0; j < 16; ++j) {
;         const int t = t0 + j; const float va = a[W - 1 + j], vc = c[W - 1 + j]; sa += va; sc += vc;
;         const float inv = 1.0f / (float)((t + 1 < W) ? t + 1 : W);
;         mpa[(size_t)t * DM] = f2bf(sa * inv - va); mpb[(size_t)t * DM] = f2bf(sc * inv - vc);
;         sa -= a[j]; sc -= c[j];
;     }
; }
	s_add_u32 s28, s28, 0x800
	s_addc_u32 s29, s29, 0
	s_cmp_eq_u32 s12, 0
	s_cselect_b32 s32, 0x3e4ccccd, s56
	v_add_f32_e32 v4, v4, v23
	v_add_f32_e32 v5, v5, v93
	v_fma_f32 v6, s32, v4, -v23
	v_fma_f32 v7, s32, v5, -v93
	v_sub_f32_e32 v4, v4, v16
	v_sub_f32_e32 v5, v5, v86
	v_cvt_pk_bf16_f32 v117, v6, v7
	global_store_dword v0, v117, s[28:29]
	s_add_u32 s28, s28, 0x800
	s_addc_u32 s29, s29, 0
	s_cmp_eq_u32 s12, 0
	s_cselect_b32 s32, 0x3e2aaaab, s56
	v_add_f32_e32 v4, v4, v24
	v_add_f32_e32 v5, v5, v94
	v_fma_f32 v6, s32, v4, -v24
	v_fma_f32 v7, s32, v5, -v94
	v_sub_f32_e32 v4, v4, v17
	v_sub_f32_e32 v5, v5, v87
	v_cvt_pk_bf16_f32 v118, v6, v7
	global_store_dword v0, v118, s[28:29]
	s_add_u32 s28, s28, 0x800
	s_addc_u32 s29, s29, 0
	s_cmp_eq_u32 s12, 0
	s_cselect_b32 s32, 0x3e124925, s56
	v_add_f32_e32 v4, v4, v25
	v_add_f32_e32 v5, v5, v95
	v_fma_f32 v6, s32, v4, -v25
	v_fma_f32 v7, s32, v5, -v95
	v_sub_f32_e32 v4, v4, v18
	v_sub_f32_e32 v5, v5, v88
	v_cvt_pk_bf16_f32 v119, v6, v7
	global_store_dword v0, v119, s[28:29]
	s_add_u32 s28, s28, 0x800
	s_addc_u32 s29, s29, 0
	v_add_f32_e32 v4, v4, v26
	v_add_f32_e32 v5, v5, v96
	v_fma_f32 v6, s56, v4, -v26
	v_fma_f32 v7, s56, v5, -v96
	v_sub_f32_e32 v4, v4, v19
	v_sub_f32_e32 v5, v5, v89
	v_cvt_pk_bf16_f32 v120, v6, v7
	global_store_dword v0, v120, s[28:29]
	s_add_u32 s28, s28, 0x800
	s_addc_u32 s29, s29, 0
	v_add_f32_e32 v4, v4, v27
	v_add_f32_e32 v5, v5, v97
	v_fma_f32 v6, s56, v4, -v27
	v_fma_f32 v7, s56, v5, -v97
	v_sub_f32_e32 v4, v4, v20
	v_sub_f32_e32 v5, v5, v90
	v_cvt_pk_bf16_f32 v121, v6, v7
	global_store_dword v0, v121, s[28:29]
	s_add_u32 s28, s28, 0x800
	s_addc_u32 s29, s29, 0
	v_add_f32_e32 v4, v4, v28
	v_add_f32_e32 v5, v5, v98
	v_fma_f32 v6, s56, v4, -v28
	v_fma_f32 v7, s56, v5, -v98
	v_sub_f32_e32 v4, v4, v21
	v_sub_f32_e32 v5, v5, v91
	v_cvt_pk_bf16_f32 v122, v6, v7
	global_store_dword v0, v122, s[28:29]
	s_add_u32 s28, s28, 0x800
	s_addc_u32 s29, s29, 0
	v_add_f32_e32 v4, v4, v29
	v_add_f32_e32 v5, v5, v99
	v_fma_f32 v6, s56, v4, -v29
	v_fma_f32 v7, s56, v5, -v99
	v_sub_f32_e32 v4, v4, v22
	v_sub_f32_e32 v5, v5, v92
	v_cvt_pk_bf16_f32 v123, v6, v7
	global_store_dword v0, v123, s[28:29]
	s_add_u32 s28, s28, 0x800
	s_addc_u32 s29, s29, 0
	v_add_f32_e32 v4, v4, v30
	v_add_f32_e32 v5, v5, v100
	v_fma_f32 v6, s56, v4, -v30
	v_fma_f32 v7, s56, v5, -v100
	v_sub_f32_e32 v4, v4, v23
	v_sub_f32_e32 v5, v5, v93
	v_cvt_pk_bf16_f32 v124, v6, v7
	global_store_dword v0, v124, s[28:29]
	s_add_u32 s28, s28, 0x800
	s_addc_u32 s29, s29, 0
	v_add_f32_e32 v4, v4, v31
	v_add_f32_e32 v5, v5, v101
	v_fma_f32 v6, s56, v4, -v31
	v_fma_f32 v7, s56, v5, -v101
	v_sub_f32_e32 v4, v4, v24
	v_sub_f32_e32 v5, v5, v94
	v_cvt_pk_bf16_f32 v125, v6, v7
	global_store_dword v0, v125, s[28:29]
	s_add_u32 s28, s28, 0x800
	s_addc_u32 s29, s29, 0
	v_add_f32_e32 v4, v4, v32
	v_add_f32_e32 v5, v5, v102
	v_fma_f32 v6, s56, v4, -v32
	v_fma_f32 v7, s56, v5, -v102
	v_sub_f32_e32 v4, v4, v25
	v_sub_f32_e32 v5, v5, v95
	v_cvt_pk_bf16_f32 v126, v6, v7
	global_store_dword v0, v126, s[28:29]
	s_add_u32 s28, s28, 0x800
	s_addc_u32 s29, s29, 0
	v_add_f32_e32 v4, v4, v33
	v_add_f32_e32 v5, v5, v103
	v_fma_f32 v6, s56, v4, -v33
	v_fma_f32 v7, s56, v5, -v103
	v_sub_f32_e32 v4, v4, v26
	v_sub_f32_e32 v5, v5, v96
	v_cvt_pk_bf16_f32 v127, v6, v7
	global_store_dword v0, v127, s[28:29]
	s_add_u32 s28, s28, 0x800
	s_addc_u32 s29, s29, 0
	v_add_f32_e32 v4, v4, v34
	v_add_f32_e32 v5, v5, v104
	v_fma_f32 v6, s56, v4, -v34
	v_fma_f32 v7, s56, v5, -v104
	v_sub_f32_e32 v4, v4, v27
	v_sub_f32_e32 v5, v5, v97
	v_cvt_pk_bf16_f32 v128, v6, v7
	global_store_dword v0, v128, s[28:29]
	s_add_u32 s18, s18, 0x1000000
	s_addc_u32 s19, s19, 0
	s_sub_u32 s57, s57, 1
	s_cmp_lg_u32 s57, 0
	s_cbranch_scc1 .Lpool_w8_loop
	s_branch .LBB0_464
.Lpool_w4:
	s_mov_b32 s56, 0x3e800000
.Lpool_w4_loop:
	s_sub_u32 s26, s18, 0x1800
	s_subb_u32 s27, s19, 0
	global_load_dword v12, v0, s[26:27]
	s_add_u32 s26, s26, 0x800
	s_addc_u32 s27, s27, 0
	global_load_dword v13, v0, s[26:27]
	s_add_u32 s26, s26, 0x800
	s_addc_u32 s27, s27, 0
	global_load_dword v14, v0, s[26:27]
	s_add_u32 s26, s26, 0x800
	s_addc_u32 s27, s27, 0
	global_load_dword v15, v0, s[26:27]
	s_add_u32 s26, s26, 0x800
	s_addc_u32 s27, s27, 0
	global_load_dword v16, v0, s[26:27]
	s_add_u32 s26, s26, 0x800
	s_addc_u32 s27, s27, 0
	global_load_dword v17, v0, s[26:27]
	s_add_u32 s26, s26, 0x800
	s_addc_u32 s27, s27, 0
	global_load_dword v18, v0, s[26:27]
	s_add_u32 s26, s26, 0x800
	s_addc_u32 s27, s27, 0
	global_load_dword v19, v0, s[26:27]
	s_add_u32 s26, s26, 0x800
	s_addc_u32 s27, s27, 0
	global_load_dword v20, v0, s[26:27]
	s_add_u32 s26, s26, 0x800
	s_addc_u32 s27, s27, 0
	global_load_dword v21, v0, s[26:27]
	s_add_u32 s26, s26, 0x800
	s_addc_u32 s27, s27, 0
	global_load_dword v22, v0, s[26:27]
	s_add_u32 s26, s26, 0x800
	s_addc_u32 s27, s27, 0
	global_load_dword v23, v0, s[26:27]
	s_add_u32 s26, s26, 0x800
	s_addc_u32 s27, s27, 0
	global_load_dword v24, v0, s[26:27]
	s_add_u32 s26, s26, 0x800
	s_addc_u32 s27, s27, 0
	global_load_dword v25, v0, s[26:27]
	s_add_u32 s26, s26, 0x800
	s_addc_u32 s27, s27, 0
	global_load_dword v26, v0, s[26:27]
	s_add_u32 s26, s26, 0x800
	s_addc_u32 s27, s27, 0
	global_load_dword v27, v0, s[26:27]
	s_add_u32 s26, s26, 0x800
	s_addc_u32 s27, s27, 0
	global_load_dword v28, v0, s[26:27]
	s_add_u32 s26, s26, 0x800
	s_addc_u32 s27, s27, 0
	global_load_dword v29, v0, s[26:27]
	s_add_u32 s26, s26, 0x800
	s_addc_u32 s27, s27, 0
	global_load_dword v30, v0, s[26:27]
	s_add_u32 s28, s18, 0x8000000
	s_addc_u32 s29, s19, 0
	s_waitcnt vmcnt(0)
; __device__ __forceinline__ bf16_t f2bf(float f) { unsigned u = __float_as_uint(f); u += 0x7FFFu + ((u >> 16) & 1u); return (bf16_t)(u >> 16); }
; __device__ __forceinline__ float bf2f(bf16_t v) { return __uint_as_float(((unsigned)v) << 16); }
; template <int W> __device__ __forceinline__ void pool_round2(const bf16_t* zpa, bf16_t* mpa, const bf16_t* zpb, bf16_t* mpb, int t0) {
;     float a[W - 1 + 16], c[W - 1 + 16];
; #pragma unroll
;     for (int i = 0; i < W - 1 + 16; ++i) { const int t = t0 - (W - 1) + i; a[i] = (t >= 0) ? bf2f(zpa[(size_t)t * DM]) : 0.f; c[i] = (t >= 0) ? bf2f(zpb[(size_t)t * DM]) : 0.f; }
;     float sa = 0.f, sc = 0.f;
; #pragma unroll
;     for (int i = 0; i < W - 1; ++i) { sa += a[i]; sc += c[i]; }
; #pragma unroll
;     for (int j = 0; j < 16; ++j) {
;         const int t = t0 + j; const float va = a[W - 1 + j], vc = c[W - 1 + j]; sa += va; sc += vc;
;         const float inv = 1.0f / (float)((t + 1 < W) ? t + 1 : W);
;         mpa[(size_t)t * DM] = f2bf(sa * inv - va); mpb[(size_t)t * DM] = f2bf(sc * inv - vc);
;         sa -= a[j]; sc -= c[j];
;     }
; }
	v_and_b32_e32 v12, s14, v12
	v_and_b32_e32 v13, s14, v13
	v_and_b32_e32 v14, s14, v14
	v_and_b32_e32 v82, 0xffff0000, v12
	v_lshlrev_b32_e32 v12, 16, v12
	v_and_b32_e32 v83, 0xffff0000, v13
	v_lshlrev_b32_e32 v13, 16, v13
	v_and_b32_e32 v84, 0xffff0000, v14
	v_lshlrev_b32_e32 v14, 16, v14
	v_and_b32_e32 v85, 0xffff0000, v15
	v_lshlrev_b32_e32 v15, 16, v15
	v_and_b32_e32 v86, 0xffff0000, v16
	v_lshlrev_b32_e32 v16, 16, v16
	v_and_b32_e32 v87, 0xffff0000, v17
	v_lshlrev_b32_e32 v17, 16, v17
	v_and_b32_e32 v88, 0xffff0000, v18
	v_lshlrev_b32_e32 v18, 16, v18
	v_and_b32_e32 v89, 0xffff0000, v19
	v_lshlrev_b32_e32 v19, 16, v19
	v_and_b32_e32 v90, 0xffff0000, v20
	v_lshlrev_b32_e32 v20, 16, v20
	v_and_b32_e32 v91, 0xffff0000, v21
	v_lshlrev_b32_e32 v21, 16, v21
	v_and_b32_e32 v92, 0xffff0000, v22
	v_lshlrev_b32_e32 v22, 16, v22
	v_and_b32_e32 v93, 0xffff0000, v23
	v_lshlrev_b32_e32 v23, 16, v23
	v_and_b32_e32 v94, 0xffff0000, v24
	v_lshlrev_b32_e32 v24, 16, v24
	v_and_b32_e32 v95, 0xffff0000, v25
	v_lshlrev_b32_e32 v25, 16, v25
	v_and_b32_e32 v96, 0xffff0000, v26
	v_lshlrev_b32_e32 v26, 16, v26
	v_and_b32_e32 v97, 0xffff0000, v27
	v_lshlrev_b32_e32 v27, 16, v27
	v_and_b32_e32 v98, 0xffff0000, v28
	v_lshlrev_b32_e32 v28, 16, v28
	v_and_b32_e32 v99, 0xffff0000, v29
	v_lshlrev_b32_e32 v29, 16, v29
	v_and_b32_e32 v100, 0xffff0000, v30
	v_lshlrev_b32_e32 v30, 16, v30
	v_add_f32_e32 v4, 0, v12
	v_add_f32_e32 v5, 0, v82
	v_add_f32_e32 v4, v4, v13
	v_add_f32_e32 v5, v5, v83
	v_add_f32_e32 v4, v4, v14
	v_add_f32_e32 v5, v5, v84
	s_cmp_eq_u32 s12, 0
	s_cselect_b32 s32, 0x3f800000, s56
	v_add_f32_e32 v4, v4, v15
	v_add_f32_e32 v5, v5, v85
	v_fma_f32 v6, s32, v4, -v15
	v_fma_f32 v7, s32, v5, -v85
	v_sub_f32_e32 v4, v4, v12
	v_sub_f32_e32 v5, v5, v82
	v_cvt_pk_bf16_f32 v113, v6, v7
	global_store_dword v0, v113, s[28:29]
	s_add_u32 s28, s28, 0x800
	s_addc_u32 s29, s29, 0
	s_cmp_eq_u32 s12, 0
	s_cselect_b32 s32, 0x3f000000, s56
	v_add_f32_e32 v4, v4, v16
	v_add_f32_e32 v5, v5, v86
	v_fma_f32 v6, s32, v4, -v16
	v_fma_f32 v7, s32, v5, -v86
	v_sub_f32_e32 v4, v4, v13
	v_sub_f32_e32 v5, v5, v83
	v_cvt_pk_bf16_f32 v114, v6, v7
	global_store_dword v0, v114, s[28:29]
	s_add_u32 s28, s28, 0x800
	s_addc_u32 s29, s29, 0
	s_cmp_eq_u32 s12, 0
	s_cselect_b32 s32, 0x3eaaaaab, s56
	v_add_f32_e32 v4, v4, v17
	v_add_f32_e32 v5, v5, v87
	v_fma_f32 v6, s32, v4, -v17
	v_fma_f32 v7, s32, v5, -v87
	v_sub_f32_e32 v4, v4, v14
	v_sub_f32_e32 v5, v5, v84
	v_cvt_pk_bf16_f32 v115, v6, v7
	global_store_dword v0, v115, s[28:29]
	s_add_u32 s28, s28, 0x800
	s_addc_u32 s29, s29, 0
	v_add_f32_e32 v4, v4, v18
	v_add_f32_e32 v5, v5, v88
	v_fma_f32 v6, s56, v4, -v18
	v_fma_f32 v7, s56, v5, -v88
	v_sub_f32_e32 v4, v4, v15
	v_sub_f32_e32 v5, v5, v85
	v_cvt_pk_bf16_f32 v116, v6, v7
	global_store_dword v0, v116, s[28:29]
	s_add_u32 s28, s28, 0x800
	s_addc_u32 s29, s29, 0
	v_add_f32_e32 v4, v4, v19
	v_add_f32_e32 v5, v5, v89
	v_fma_f32 v6, s56, v4, -v19
	v_fma_f32 v7, s56, v5, -v89
	v_sub_f32_e32 v4, v4, v16
	v_sub_f32_e32 v5, v5, v86
	v_cvt_pk_bf16_f32 v117, v6, v7
	global_store_dword v0, v117, s[28:29]
	s_add_u32 s28, s28, 0x800
	s_addc_u32 s29, s29, 0
	v_add_f32_e32 v4, v4, v20
	v_add_f32_e32 v5, v5, v90
	v_fma_f32 v6, s56, v4, -v20
	v_fma_f32 v7, s56, v5, -v90
	v_sub_f32_e32 v4, v4, v17
	v_sub_f32_e32 v5, v5, v87
	v_cvt_pk_bf16_f32 v118, v6, v7
	global_store_dword v0, v118, s[28:29]
	s_add_u32 s28, s28, 0x800
	s_addc_u32 s29, s29, 0
	v_add_f32_e32 v4, v4, v21
	v_add_f32_e32 v5, v5, v91
	v_fma_f32 v6, s56, v4, -v21
	v_fma_f32 v7, s56, v5, -v91
	v_sub_f32_e32 v4, v4, v18
	v_sub_f32_e32 v5, v5, v88
	v_cvt_pk_bf16_f32 v119, v6, v7
	global_store_dword v0, v119, s[28:29]
	s_add_u32 s28, s28, 0x800
	s_addc_u32 s29, s29, 0
	v_add_f32_e32 v4, v4, v22
	v_add_f32_e32 v5, v5, v92
	v_fma_f32 v6, s56, v4, -v22
	v_fma_f32 v7, s56, v5, -v92
	v_sub_f32_e32 v4, v4, v19
	v_sub_f32_e32 v5, v5, v89
	v_cvt_pk_bf16_f32 v120, v6, v7
	global_store_dword v0, v120, s[28:29]
	s_add_u32 s28, s28, 0x800
	s_addc_u32 s29, s29, 0
	v_add_f32_e32 v4, v4, v23
	v_add_f32_e32 v5, v5, v93
	v_fma_f32 v6, s56, v4, -v23
	v_fma_f32 v7, s56, v5, -v93
	v_sub_f32_e32 v4, v4, v20
	v_sub_f32_e32 v5, v5, v90
	v_cvt_pk_bf16_f32 v121, v6, v7
	global_store_dword v0, v121, s[28:29]
	s_add_u32 s28, s28, 0x800
	s_addc_u32 s29, s29, 0
	v_add_f32_e32 v4, v4, v24
	v_add_f32_e32 v5, v5, v94
	v_fma_f32 v6, s56, v4, -v24
	v_fma_f32 v7, s56, v5, -v94
	v_sub_f32_e32 v4, v4, v21
	v_sub_f32_e32 v5, v5, v91
	v_cvt_pk_bf16_f32 v122, v6, v7
	global_store_dword v0, v122, s[28:29]
	s_add_u32 s28, s28, 0x800
	s_addc_u32 s29, s29, 0
	v_add_f32_e32 v4, v4, v25
	v_add_f32_e32 v5, v5, v95
	v_fma_f32 v6, s56, v4, -v25
	v_fma_f32 v7, s56, v5, -v95
	v_sub_f32_e32 v4, v4, v22
	v_sub_f32_e32 v5, v5, v92
	v_cvt_pk_bf16_f32 v123, v6, v7
	global_store_dword v0, v123, s[28:29]
	s_add_u32 s28, s28, 0x800
	s_addc_u32 s29, s29, 0
	v_add_f32_e32 v4, v4, v26
	v_add_f32_e32 v5, v5, v96
	v_fma_f32 v6, s56, v4, -v26
	v_fma_f32 v7, s56, v5, -v96
	v_sub_f32_e32 v4, v4, v23
	v_sub_f32_e32 v5, v5, v93
	v_cvt_pk_bf16_f32 v124, v6, v7
	global_store_dword v0, v124, s[28:29]
	s_add_u32 s28, s28, 0x800
	s_addc_u32 s29, s29, 0
	v_add_f32_e32 v4, v4, v27
	v_add_f32_e32 v5, v5, v97
	v_fma_f32 v6, s56, v4, -v27
	v_fma_f32 v7, s56, v5, -v97
	v_sub_f32_e32 v4, v4, v24
	v_sub_f32_e32 v5, v5, v94
	v_cvt_pk_bf16_f32 v125, v6, v7
	global_store_dword v0, v125, s[28:29]
	s_add_u32 s28, s28, 0x800
	s_addc_u32 s29, s29, 0
	v_add_f32_e32 v4, v4, v28
	v_add_f32_e32 v5, v5, v98
	v_fma_f32 v6, s56, v4, -v28
	v_fma_f32 v7, s56, v5, -v98
	v_sub_f32_e32 v4, v4, v25
	v_sub_f32_e32 v5, v5, v95
	v_cvt_pk_bf16_f32 v126, v6, v7
	global_store_dword v0, v126, s[28:29]
	s_add_u32 s28, s28, 0x800
	s_addc_u32 s29, s29, 0
	v_add_f32_e32 v4, v4, v29
	v_add_f32_e32 v5, v5, v99
	v_fma_f32 v6, s56, v4, -v29
	v_fma_f32 v7, s56, v5, -v99
	v_sub_f32_e32 v4, v4, v26
	v_sub_f32_e32 v5, v5, v96
	v_cvt_pk_bf16_f32 v127, v6, v7
	global_store_dword v0, v127, s[28:29]
	s_add_u32 s28, s28, 0x800
	s_addc_u32 s29, s29, 0
	v_add_f32_e32 v4, v4, v30
	v_add_f32_e32 v5, v5, v100
	v_fma_f32 v6, s56, v4, -v30
	v_fma_f32 v7, s56, v5, -v100
	v_sub_f32_e32 v4, v4, v27
	v_sub_f32_e32 v5, v5, v97
	v_cvt_pk_bf16_f32 v128, v6, v7
	global_store_dword v0, v128, s[28:29]
	s_add_u32 s18, s18, 0x1000000
	s_addc_u32 s19, s19, 0
	s_sub_u32 s57, s57, 1
	s_cmp_lg_u32 s57, 0
	s_cbranch_scc1 .Lpool_w4_loop
	s_branch .LBB0_464
; __device__ __forceinline__ float bf2f(bf16_t v) { return __uint_as_float(((unsigned)v) << 16); }
; template <int W> __device__ __forceinline__ void pool_round2(const bf16_t* zpa, bf16_t* mpa, const bf16_t* zpb, bf16_t* mpb, int t0) {
;     float a[W - 1 + 16], c[W - 1 + 16];
; #pragma unroll
;     for (int i = 0; i < W - 1 + 16; ++i) { const int t = t0 - (W - 1) + i; a[i] = (t >= 0) ? bf2f(zpa[(size_t)t * DM]) : 0.f; c[i] = (t >= 0) ? bf2f(zpb[(size_t)t * DM]) : 0.f; }
;     float sa = 0.f, sc = 0.f;
; #pragma unroll
;     for (int i = 0; i < W - 1; ++i) { sa += a[i]; sc += c[i]; }
.Lpool_w2:
	s_mov_b32 s56, 0x3f000000
.Lpool_w2_loop:
	s_sub_u32 s26, s18, 0x800
	s_subb_u32 s27, s19, 0
	global_load_dword v12, v0, s[26:27]
	s_add_u32 s26, s26, 0x800
	s_addc_u32 s27, s27, 0
	global_load_dword v13, v0, s[26:27]
	s_add_u32 s26, s26, 0x800
	s_addc_u32 s27, s27, 0
	global_load_dword v14, v0, s[26:27]
	s_add_u32 s26, s26, 0x800
	s_addc_u32 s27, s27, 0
	global_load_dword v15, v0, s[26:27]
	s_add_u32 s26, s26, 0x800
	s_addc_u32 s27, s27, 0
	global_load_dword v16, v0, s[26:27]
	s_add_u32 s26, s26, 0x800
	s_addc_u32 s27, s27, 0
	global_load_dword v17, v0, s[26:27]
	s_add_u32 s26, s26, 0x800
	s_addc_u32 s27, s27, 0
	global_load_dword v18, v0, s[26:27]
	s_add_u32 s26, s26, 0x800
	s_addc_u32 s27, s27, 0
	global_load_dword v19, v0, s[26:27]
	s_add_u32 s26, s26, 0x800
	s_addc_u32 s27, s27, 0
	global_load_dword v20, v0, s[26:27]
	s_add_u32 s26, s26, 0x800
	s_addc_u32 s27, s27, 0
	global_load_dword v21, v0, s[26:27]
	s_add_u32 s26, s26, 0x800
	s_addc_u32 s27, s27, 0
	global_load_dword v22, v0, s[26:27]
	s_add_u32 s26, s26, 0x800
	s_addc_u32 s27, s27, 0
	global_load_dword v23, v0, s[26:27]
	s_add_u32 s26, s26, 0x800
	s_addc_u32 s27, s27, 0
	global_load_dword v24, v0, s[26:27]
	s_add_u32 s26, s26, 0x800
	s_addc_u32 s27, s27, 0
	global_load_dword v25, v0, s[26:27]
	s_add_u32 s26, s26, 0x800
	s_addc_u32 s27, s27, 0
	global_load_dword v26, v0, s[26:27]
	s_add_u32 s26, s26, 0x800
	s_addc_u32 s27, s27, 0
	global_load_dword v27, v0, s[26:27]
	s_add_u32 s26, s26, 0x800
	s_addc_u32 s27, s27, 0
	global_load_dword v28, v0, s[26:27]
	s_add_u32 s28, s18, 0x8000000
	s_addc_u32 s29, s19, 0
	s_waitcnt vmcnt(0)
; __device__ __forceinline__ bf16_t f2bf(float f) { unsigned u = __float_as_uint(f); u += 0x7FFFu + ((u >> 16) & 1u); return (bf16_t)(u >> 16); }
; __device__ __forceinline__ float bf2f(bf16_t v) { return __uint_as_float(((unsigned)v) << 16); }
; template <int W> __device__ __forceinline__ void pool_round2(const bf16_t* zpa, bf16_t* mpa, const bf16_t* zpb, bf16_t* mpb, int t0) {
;     float a[W - 1 + 16], c[W - 1 + 16];
; #pragma unroll
;     for (int i = 0; i < W - 1 + 16; ++i) { const int t = t0 - (W - 1) + i; a[i] = (t >= 0) ? bf2f(zpa[(size_t)t * DM]) : 0.f; c[i] = (t >= 0) ? bf2f(zpb[(size_t)t * DM]) : 0.f; }
;     float sa = 0.f, sc = 0.f;
; #pragma unroll
;     for (int i = 0; i < W - 1; ++i) { sa += a[i]; sc += c[i]; }
; #pragma unroll
;     for (int j = 0; j < 16; ++j) {
;         const int t = t0 + j; const float va = a[W - 1 + j], vc = c[W - 1 + j]; sa += va; sc += vc;
;         const float inv = 1.0f / (float)((t + 1 < W) ? t + 1 : W);
;         mpa[(size_t)t * DM] = f2bf(sa * inv - va); mpb[(size_t)t * DM] = f2bf(sc * inv - vc);
;         sa -= a[j]; sc -= c[j];
;     }
; }
	v_and_b32_e32 v12, s14, v12
	v_and_b32_e32 v82, 0xffff0000, v12
	v_lshlrev_b32_e32 v12, 16, v12
	v_and_b32_e32 v83, 0xffff0000, v13
	v_lshlrev_b32_e32 v13, 16, v13
	v_and_b32_e32 v84, 0xffff0000, v14
	v_lshlrev_b32_e32 v14, 16, v14
	v_and_b32_e32 v85, 0xffff0000, v15
	v_lshlrev_b32_e32 v15, 16, v15
	v_and_b32_e32 v86, 0xffff0000, v16
	v_lshlrev_b32_e32 v16, 16, v16
	v_and_b32_e32 v87, 0xffff0000, v17
	v_lshlrev_b32_e32 v17, 16, v17
	v_and_b32_e32 v88, 0xffff0000, v18
	v_lshlrev_b32_e32 v18, 16, v18
	v_and_b32_e32 v89, 0xffff0000, v19
	v_lshlrev_b32_e32 v19, 16, v19
	v_and_b32_e32 v90, 0xffff0000, v20
	v_lshlrev_b32_e32 v20, 16, v20
	v_and_b32_e32 v91, 0xffff0000, v21
	v_lshlrev_b32_e32 v21, 16, v21
	v_and_b32_e32 v92, 0xffff0000, v22
	v_lshlrev_b32_e32 v22, 16, v22
	v_and_b32_e32 v93, 0xffff0000, v23
	v_lshlrev_b32_e32 v23, 16, v23
	v_and_b32_e32 v94, 0xffff0000, v24
	v_lshlrev_b32_e32 v24, 16, v24
	v_and_b32_e32 v95, 0xffff0000, v25
	v_lshlrev_b32_e32 v25, 16, v25
	v_and_b32_e32 v96, 0xffff0000, v26
	v_lshlrev_b32_e32 v26, 16, v26
	v_and_b32_e32 v97, 0xffff0000, v27
	v_lshlrev_b32_e32 v27, 16, v27
	v_and_b32_e32 v98, 0xffff0000, v28
	v_lshlrev_b32_e32 v28, 16, v28
	v_add_f32_e32 v4, 0, v12
	v_add_f32_e32 v5, 0, v82
	s_cmp_eq_u32 s12, 0
	s_cselect_b32 s32, 0x3f800000, s56
	v_add_f32_e32 v4, v4, v13
	v_add_f32_e32 v5, v5, v83
	v_fma_f32 v6, s32, v4, -v13
	v_fma_f32 v7, s32, v5, -v83
	v_sub_f32_e32 v4, v4, v12
	v_sub_f32_e32 v5, v5, v82
	v_cvt_pk_bf16_f32 v113, v6, v7
	global_store_dword v0, v113, s[28:29]
	s_add_u32 s28, s28, 0x800
	s_addc_u32 s29, s29, 0
	v_add_f32_e32 v4, v4, v14
	v_add_f32_e32 v5, v5, v84
	v_fma_f32 v6, s56, v4, -v14
	v_fma_f32 v7, s56, v5, -v84
	v_sub_f32_e32 v4, v4, v13
	v_sub_f32_e32 v5, v5, v83
	v_cvt_pk_bf16_f32 v114, v6, v7
	global_store_dword v0, v114, s[28:29]
	s_add_u32 s28, s28, 0x800
	s_addc_u32 s29, s29, 0
	v_add_f32_e32 v4, v4, v15
	v_add_f32_e32 v5, v5, v85
	v_fma_f32 v6, s56, v4, -v15
	v_fma_f32 v7, s56, v5, -v85
	v_sub_f32_e32 v4, v4, v14
	v_sub_f32_e32 v5, v5, v84
	v_cvt_pk_bf16_f32 v115, v6, v7
	global_store_dword v0, v115, s[28:29]
	s_add_u32 s28, s28, 0x800
	s_addc_u32 s29, s29, 0
	v_add_f32_e32 v4, v4, v16
	v_add_f32_e32 v5, v5, v86
	v_fma_f32 v6, s56, v4, -v16
	v_fma_f32 v7, s56, v5, -v86
	v_sub_f32_e32 v4, v4, v15
	v_sub_f32_e32 v5, v5, v85
	v_cvt_pk_bf16_f32 v116, v6, v7
	global_store_dword v0, v116, s[28:29]
	s_add_u32 s28, s28, 0x800
	s_addc_u32 s29, s29, 0
	v_add_f32_e32 v4, v4, v17
	v_add_f32_e32 v5, v5, v87
	v_fma_f32 v6, s56, v4, -v17
	v_fma_f32 v7, s56, v5, -v87
	v_sub_f32_e32 v4, v4, v16
	v_sub_f32_e32 v5, v5, v86
	v_cvt_pk_bf16_f32 v117, v6, v7
	global_store_dword v0, v117, s[28:29]
	s_add_u32 s28, s28, 0x800
	s_addc_u32 s29, s29, 0
	v_add_f32_e32 v4, v4, v18
	v_add_f32_e32 v5, v5, v88
	v_fma_f32 v6, s56, v4, -v18
	v_fma_f32 v7, s56, v5, -v88
	v_sub_f32_e32 v4, v4, v17
	v_sub_f32_e32 v5, v5, v87
	v_cvt_pk_bf16_f32 v118, v6, v7
	global_store_dword v0, v118, s[28:29]
	s_add_u32 s28, s28, 0x800
	s_addc_u32 s29, s29, 0
	v_add_f32_e32 v4, v4, v19
	v_add_f32_e32 v5, v5, v89
	v_fma_f32 v6, s56, v4, -v19
	v_fma_f32 v7, s56, v5, -v89
	v_sub_f32_e32 v4, v4, v18
	v_sub_f32_e32 v5, v5, v88
	v_cvt_pk_bf16_f32 v119, v6, v7
	global_store_dword v0, v119, s[28:29]
	s_add_u32 s28, s28, 0x800
	s_addc_u32 s29, s29, 0
	v_add_f32_e32 v4, v4, v20
	v_add_f32_e32 v5, v5, v90
	v_fma_f32 v6, s56, v4, -v20
	v_fma_f32 v7, s56, v5, -v90
	v_sub_f32_e32 v4, v4, v19
	v_sub_f32_e32 v5, v5, v89
	v_cvt_pk_bf16_f32 v120, v6, v7
	global_store_dword v0, v120, s[28:29]
	s_add_u32 s28, s28, 0x800
	s_addc_u32 s29, s29, 0
	v_add_f32_e32 v4, v4, v21
	v_add_f32_e32 v5, v5, v91
	v_fma_f32 v6, s56, v4, -v21
	v_fma_f32 v7, s56, v5, -v91
	v_sub_f32_e32 v4, v4, v20
	v_sub_f32_e32 v5, v5, v90
	v_cvt_pk_bf16_f32 v121, v6, v7
	global_store_dword v0, v121, s[28:29]
	s_add_u32 s28, s28, 0x800
	s_addc_u32 s29, s29, 0
	v_add_f32_e32 v4, v4, v22
	v_add_f32_e32 v5, v5, v92
	v_fma_f32 v6, s56, v4, -v22
	v_fma_f32 v7, s56, v5, -v92
	v_sub_f32_e32 v4, v4, v21
	v_sub_f32_e32 v5, v5, v91
	v_cvt_pk_bf16_f32 v122, v6, v7
	global_store_dword v0, v122, s[28:29]
	s_add_u32 s28, s28, 0x800
	s_addc_u32 s29, s29, 0
	v_add_f32_e32 v4, v4, v23
	v_add_f32_e32 v5, v5, v93
	v_fma_f32 v6, s56, v4, -v23
	v_fma_f32 v7, s56, v5, -v93
	v_sub_f32_e32 v4, v4, v22
	v_sub_f32_e32 v5, v5, v92
	v_cvt_pk_bf16_f32 v123, v6, v7
	global_store_dword v0, v123, s[28:29]
	s_add_u32 s28, s28, 0x800
	s_addc_u32 s29, s29, 0
	v_add_f32_e32 v4, v4, v24
	v_add_f32_e32 v5, v5, v94
	v_fma_f32 v6, s56, v4, -v24
	v_fma_f32 v7, s56, v5, -v94
	v_sub_f32_e32 v4, v4, v23
	v_sub_f32_e32 v5, v5, v93
	v_cvt_pk_bf16_f32 v124, v6, v7
	global_store_dword v0, v124, s[28:29]
	s_add_u32 s28, s28, 0x800
	s_addc_u32 s29, s29, 0
	v_add_f32_e32 v4, v4, v25
	v_add_f32_e32 v5, v5, v95
	v_fma_f32 v6, s56, v4, -v25
	v_fma_f32 v7, s56, v5, -v95
	v_sub_f32_e32 v4, v4, v24
	v_sub_f32_e32 v5, v5, v94
	v_cvt_pk_bf16_f32 v125, v6, v7
	global_store_dword v0, v125, s[28:29]
	s_add_u32 s28, s28, 0x800
	s_addc_u32 s29, s29, 0
	v_add_f32_e32 v4, v4, v26
	v_add_f32_e32 v5, v5, v96
	v_fma_f32 v6, s56, v4, -v26
	v_fma_f32 v7, s56, v5, -v96
	v_sub_f32_e32 v4, v4, v25
	v_sub_f32_e32 v5, v5, v95
	v_cvt_pk_bf16_f32 v126, v6, v7
	global_store_dword v0, v126, s[28:29]
	s_add_u32 s28, s28, 0x800
	s_addc_u32 s29, s29, 0
	v_add_f32_e32 v4, v4, v27
	v_add_f32_e32 v5, v5, v97
	v_fma_f32 v6, s56, v4, -v27
	v_fma_f32 v7, s56, v5, -v97
	v_sub_f32_e32 v4, v4, v26
	v_sub_f32_e32 v5, v5, v96
	v_cvt_pk_bf16_f32 v127, v6, v7
	global_store_dword v0, v127, s[28:29]
	s_add_u32 s28, s28, 0x800
	s_addc_u32 s29, s29, 0
	v_add_f32_e32 v4, v4, v28
	v_add_f32_e32 v5, v5, v98
	v_fma_f32 v6, s56, v4, -v28
	v_fma_f32 v7, s56, v5, -v98
	v_sub_f32_e32 v4, v4, v27
	v_sub_f32_e32 v5, v5, v97
	v_cvt_pk_bf16_f32 v128, v6, v7
	global_store_dword v0, v128, s[28:29]
	s_add_u32 s18, s18, 0x1000000
	s_addc_u32 s19, s19, 0
	s_sub_u32 s57, s57, 1
	s_cmp_lg_u32 s57, 0
	s_cbranch_scc1 .Lpool_w2_loop

; __device__ __forceinline__ unsigned cvt_pk_bf16(float lo, float hi) { const f32x2 v = {lo, hi}; return __builtin_bit_cast(unsigned, __builtin_convertvector(v, bfx2_t)); }
; __device__ __forceinline__ void conv_p(const Params& P, int l) {
;     const float* src = P.in[1] + (size_t)l * TT * 256; bf16_t* dst = (bf16_t*)(P.ws + WS_PB);
;     const size_t n8 = (size_t)TT * 256 / 8, stride = (size_t)gridDim.x * NTHREADS;
;     size_t i = (size_t)blockIdx.x * NTHREADS + threadIdx.x;
;     for (; i + 3 * stride < n8; i += 4 * stride) {
;         f32x4 a[4], b[4];
; #pragma unroll
;         for (int q = 0; q < 4; ++q) { a[q] = *(const f32x4*)(src + (i + q * stride) * 8); b[q] = *(const f32x4*)(src + (i + q * stride) * 8 + 4); }
; #pragma unroll
;         for (int q = 0; q < 4; ++q) { u32x4 w; w.x = cvt_pk_bf16(a[q][0], a[q][1]); w.y = cvt_pk_bf16(a[q][2], a[q][3]); w.z = cvt_pk_bf16(b[q][0], b[q][1]); w.w = cvt_pk_bf16(b[q][2], b[q][3]);
;             *(u32x4*)(dst + (i + q * stride) * 8) = w; }
;     }
;     for (; i < n8; i += stride) {
;         const f32x4 a = *(const f32x4*)(src + i * 8), b = *(const f32x4*)(src + i * 8 + 4);
;         u32x4 w; w.x = cvt_pk_bf16(a[0], a[1]); w.y = cvt_pk_bf16(a[2], a[3]); w.z = cvt_pk_bf16(b[0], b[1]); w.w = cvt_pk_bf16(b[2], b[3]);
;         *(u32x4*)(dst + i * 8) = w;
;     }
; }
.LBB0_465:
	s_branch .LBB0_473
	s_mul_i32 s11, s31, 0xba2e8ba3
	s_mul_hi_u32 s12, s30, 0xba2e8ba3
	s_mul_hi_u32 s10, s31, 0xba2e8ba3
	s_add_u32 s11, s11, s12
	s_mul_i32 s1, s30, 0x2e8ba2e8
	s_addc_u32 s10, s10, 0
	s_mul_hi_u32 s0, s30, 0x2e8ba2e8
	s_add_u32 s1, s1, s11
	s_addc_u32 s0, s0, 0
	s_add_u32 s0, s10, s0
	s_addc_u32 s1, 0, 0
	s_mul_i32 s11, s31, 0x2e8ba2e8
	s_mul_hi_u32 s10, s31, 0x2e8ba2e8
	s_add_u32 s0, s11, s0
	s_addc_u32 s1, s10, s1
	s_lshl_b64 s[0:1], s[0:1], 25
	s_and_b32 s0, s0, 0xfc000000
	s_waitcnt lgkmcnt(0)
	v_mov_b64_e32 v[0:1], v[166:167]
	s_mov_b64 s[10:11], exec
	v_readlane_b32 s12, v252, 29
	v_readlane_b32 s13, v252, 30
	s_and_b64 s[12:13], s[10:11], s[12:13]
	s_mov_b64 exec, s[12:13]
	s_cbranch_execz .LBB0_469
	v_readlane_b32 s16, v253, 2
	v_readlane_b32 s17, v253, 3
	v_readlane_b32 s18, v253, 4
	v_readlane_b32 s19, v253, 5
	v_readlane_b32 s20, v253, 6
	v_readlane_b32 s21, v253, 7
	v_readlane_b32 s22, v253, 8
	v_readlane_b32 s23, v253, 9
	s_mov_b64 s[16:17], s[22:23]
	v_readlane_b32 s18, v252, 17
	v_readlane_b32 s20, v252, 19
	v_readlane_b32 s22, v252, 21
	v_lshl_add_u64 v[2:3], v[172:173], 0, s[0:1]
	s_mov_b64 s[14:15], 0
	v_mov_b64_e32 v[0:1], v[166:167]
	v_readlane_b32 s19, v252, 18
	v_readlane_b32 s21, v252, 20
	v_readlane_b32 s23, v252, 22
